# attention loops: every packed f32 VALU op (v_pk_add/mul/fma_f32, 365 sites) split into two scalar f32 ops (bit-identical); on top of v022
# baseline (speedup 1.0000x reference)
.LBB0_461:
	s_waitcnt lgkmcnt(0)
	s_barrier
	v_cndmask_b32_e64 v0, 0, v186, s[6:7]
	v_fmac_f32_e32 v0, -0.5, v4
	v_exp_f32_e32 v0, v0
	v_cvt_f32_u32_e32 v188, s60
	v_mul_u32_u24_e32 v88, s60, v165
	s_add_i32 s6, s95, s62
	v_ldexp_f32 v0, v0, s96
	v_mul_f32_e32 v0, v0, v188
	v_mul_f32_e32 v72, 0x3fb8aa3b, v0
	v_add_u32_e32 v0, v166, v167
	v_mov_b32_e32 v189, v168
	ds_read_b128 v[190:193], v0
	ds_read_b128 v[156:159], v0 offset:32
	ds_read_b128 v[152:155], v0 offset:64
	ds_read_b128 v[148:151], v0 offset:96
	s_cmpk_gt_i32 s6, 0x7f
	v_cvt_f32_i32_e32 v0, v189
	v_mul_f32_e32 v9, 0, v72
	s_cselect_b64 vcc, -1, 0
	v_cndmask_b32_e32 v10, v187, v9, vcc
	v_mul_f32_e64 v8, -v72, v0
	v_fma_f32 v91, -v72, v0, v72
	ds_read_b128 v[0:3], v175
	ds_read_b128 v[4:7], v175 offset:32
	v_fma_f32 v90, 0, v72, v8
	v_fma_f32 v202, v72, s36, v8
	v_fma_f32 v203, v72, s37, v8
	v_fma_f32 v204, v72, s44, v8
	v_fma_f32 v205, v72, s45, v8
	v_fma_f32 v206, v72, s46, v8
	v_fma_f32 v207, v72, s47, v8
	v_fma_f32 v208, v72, s48, v8
	v_fma_f32 v209, v72, s49, v8
	v_fma_f32 v74, v72, s52, v8
	v_fma_f32 v75, v72, s53, v8
	v_fma_f32 v76, v72, s54, v8
	v_fma_f32 v77, v72, s55, v8
	v_fma_f32 v78, v72, s56, v8
	v_fma_f32 v79, v72, s57, v8
	v_add_f32_e64 v62, v10, v78
	v_add_f32_e64 v63, v10, v79
	v_add_f32_e64 v60, v10, v76
	v_add_f32_e64 v61, v10, v77
	v_add_f32_e64 v58, v10, v74
	v_add_f32_e64 v59, v10, v75
	v_add_f32_e64 v56, v10, v208
	v_add_f32_e64 v57, v10, v209
	v_add_f32_e64 v54, v10, v206
	v_add_f32_e64 v55, v10, v207
	v_add_f32_e64 v52, v10, v204
	v_add_f32_e64 v53, v10, v205
	v_add_f32_e64 v50, v10, v202
	v_add_f32_e64 v51, v10, v203
	v_add_f32_e64 v48, v10, v90
	v_add_f32_e64 v49, v10, v91
	s_cmpk_gt_i32 s6, 0x5f
	v_mul_f32_e32 v12, 0x42000000, v72
	s_waitcnt lgkmcnt(1)
	v_mfma_f32_32x32x16_bf16 v[48:63], v[0:3], v[190:193], v[48:63]
	s_cselect_b64 vcc, -1, 0
	v_cndmask_b32_e32 v12, v187, v12, vcc
	v_add_f32_e64 v46, v12, v78
	v_add_f32_e64 v47, v12, v79
	v_add_f32_e64 v44, v12, v76
	v_add_f32_e64 v45, v12, v77
	v_add_f32_e64 v42, v12, v74
	v_add_f32_e64 v43, v12, v75
	v_add_f32_e64 v40, v12, v208
	v_add_f32_e64 v41, v12, v209
	v_add_f32_e64 v38, v12, v206
	v_add_f32_e64 v39, v12, v207
	s_waitcnt lgkmcnt(0)
	v_mfma_f32_32x32x16_bf16 v[48:63], v[4:7], v[156:159], v[48:63]
	ds_read_b128 v[0:3], v175 offset:64
	ds_read_b128 v[4:7], v175 offset:96
	v_add_f32_e64 v36, v12, v204
	v_add_f32_e64 v37, v12, v205
	v_add_f32_e64 v34, v12, v202
	v_add_f32_e64 v35, v12, v203
	v_add_f32_e64 v32, v12, v90
	v_add_f32_e64 v33, v12, v91
	s_cmp_gt_i32 s6, 63
	v_mul_f32_e32 v12, 0x42800000, v72
	s_cselect_b64 vcc, -1, 0
	s_waitcnt lgkmcnt(1)
	v_mfma_f32_32x32x16_bf16 v[48:63], v[0:3], v[152:155], v[48:63]
	ds_read_b128 v[0:3], v176
	ds_read_b128 v[8:11], v176 offset:32
	v_cndmask_b32_e32 v12, v187, v12, vcc
	v_add_f32_e64 v30, v12, v78
	v_add_f32_e64 v31, v12, v79
	v_add_f32_e64 v28, v12, v76
	v_add_f32_e64 v29, v12, v77
	v_add_f32_e64 v26, v12, v74
	v_add_f32_e64 v27, v12, v75
	v_add_f32_e64 v24, v12, v208
	v_add_f32_e64 v25, v12, v209
	v_add_f32_e64 v22, v12, v206
	v_add_f32_e64 v23, v12, v207
	s_waitcnt lgkmcnt(1)
	v_mfma_f32_32x32x16_bf16 v[32:47], v[0:3], v[190:193], v[32:47]
	v_add_f32_e64 v20, v12, v204
	v_add_f32_e64 v21, v12, v205
	v_add_f32_e64 v18, v12, v202
	v_add_f32_e64 v19, v12, v203
	v_add_f32_e64 v16, v12, v90
	v_add_f32_e64 v17, v12, v91
	s_cmp_gt_i32 s6, 31
	s_cselect_b64 vcc, -1, 0
	s_cmp_gt_i32 s6, -1
	s_waitcnt lgkmcnt(0)
	v_mfma_f32_32x32x16_bf16 v[32:47], v[8:11], v[156:159], v[32:47]
	v_mfma_f32_32x32x16_bf16 v[48:63], v[4:7], v[148:151], v[48:63]
	ds_read_b128 v[0:3], v176 offset:64
	ds_read_b128 v[4:7], v176 offset:96
	s_waitcnt lgkmcnt(1)
	v_mfma_f32_32x32x16_bf16 v[32:47], v[0:3], v[152:155], v[32:47]
	ds_read_b128 v[0:3], v177
	ds_read_b128 v[8:11], v177 offset:32
	s_waitcnt lgkmcnt(1)
	v_mfma_f32_32x32x16_bf16 v[16:31], v[0:3], v[190:193], v[16:31]
	s_waitcnt lgkmcnt(0)
	v_mfma_f32_32x32x16_bf16 v[16:31], v[8:11], v[156:159], v[16:31]
	v_mfma_f32_32x32x16_bf16 v[32:47], v[4:7], v[148:151], v[32:47]
	ds_read_b128 v[0:3], v177 offset:64
	ds_read_b128 v[4:7], v177 offset:96
	ds_read_b128 v[64:67], v178
	ds_read_b128 v[68:71], v178 offset:32
	s_waitcnt lgkmcnt(3)
	v_mfma_f32_32x32x16_bf16 v[16:31], v[0:3], v[152:155], v[16:31]
	v_mul_f32_e32 v0, 0x42c00000, v72
	v_cndmask_b32_e32 v0, v187, v0, vcc
	v_add_f32_e64 v14, v0, v78
	v_add_f32_e64 v15, v0, v79
	v_add_f32_e64 v12, v0, v76
	v_add_f32_e64 v13, v0, v77
	v_add_f32_e64 v10, v0, v74
	v_add_f32_e64 v11, v0, v75
	v_add_f32_e64 v8, v0, v208
	v_add_f32_e64 v9, v0, v209
	v_add_f32_e64 v2, v0, v202
	v_add_f32_e64 v3, v0, v203
	s_waitcnt lgkmcnt(2)
	v_mfma_f32_32x32x16_bf16 v[16:31], v[4:7], v[148:151], v[16:31]
	v_add_f32_e64 v6, v0, v206
	v_add_f32_e64 v7, v0, v207
	v_add_f32_e64 v4, v0, v204
	v_add_f32_e64 v5, v0, v205
	v_add_f32_e64 v1, v0, v91
	v_add_f32_e64 v0, v0, v90
	s_cselect_b64 vcc, -1, 0
	s_waitcnt lgkmcnt(1)
	v_mfma_f32_32x32x16_bf16 v[0:15], v[64:67], v[190:193], v[0:15]
	s_waitcnt lgkmcnt(0)
	v_mfma_f32_32x32x16_bf16 v[0:15], v[68:71], v[156:159], v[0:15]
	ds_read_b128 v[64:67], v178 offset:64
	ds_read_b128 v[68:71], v178 offset:96
	ds_read_b128 v[194:197], v179
	ds_read_b128 v[198:201], v179 offset:32
	s_waitcnt lgkmcnt(3)
	v_mfma_f32_32x32x16_bf16 v[0:15], v[64:67], v[152:155], v[0:15]
	v_mul_f32_e32 v64, 0x43000000, v72
	v_cndmask_b32_e32 v64, v187, v64, vcc
	v_add_f32_e64 v78, v64, v78
	v_add_f32_e64 v79, v64, v79
	v_add_f32_e64 v76, v64, v76
	v_add_f32_e64 v77, v64, v77
	v_add_f32_e64 v74, v64, v74
	v_add_f32_e64 v75, v64, v75
	v_add_f32_e64 v72, v64, v208
	v_add_f32_e64 v73, v64, v209
	v_add_f32_e64 v66, v64, v202
	v_add_f32_e64 v67, v64, v203
	s_waitcnt lgkmcnt(2)
	v_mfma_f32_32x32x16_bf16 v[0:15], v[68:71], v[148:151], v[0:15]
	v_add_f32_e64 v70, v64, v206
	v_add_f32_e64 v71, v64, v207
	v_add_f32_e64 v68, v64, v204
	v_add_f32_e64 v69, v64, v205
	v_add_f32_e64 v65, v64, v91
	v_add_f32_e64 v64, v64, v90
	s_waitcnt lgkmcnt(1)
	s_nop 0
	v_mfma_f32_32x32x16_bf16 v[64:79], v[194:197], v[190:193], v[64:79]
	s_waitcnt lgkmcnt(0)
	v_mfma_f32_32x32x16_bf16 v[64:79], v[198:201], v[156:159], v[64:79]
	ds_read_b128 v[156:159], v179 offset:64
	ds_read_b128 v[190:193], v179 offset:96
	s_waitcnt lgkmcnt(1)
	v_mfma_f32_32x32x16_bf16 v[64:79], v[156:159], v[152:155], v[64:79]
	s_waitcnt lgkmcnt(0)
	v_mfma_f32_32x32x16_bf16 v[64:79], v[190:193], v[148:151], v[64:79]
	s_movk_i32 s0, 0x81
	v_cmp_gt_i32_e32 vcc, s0, v189
	s_movk_i32 s0, 0x7f
	v_cmp_lt_i32_e64 s[0:1], s0, v189
	v_cndmask_b32_e32 v48, v187, v48, vcc
	s_nop 6
	v_cndmask_b32_e32 v153, v65, v187, vcc
	v_cndmask_b32_e64 v152, v187, v64, s[0:1]
	s_movk_i32 s0, 0x82
	v_cmp_gt_i32_e64 s[0:1], s0, v189
	v_cmp_gt_i32_e32 vcc, s65, v189
	s_nop 0
	v_cndmask_b32_e64 v49, v187, v49, s[0:1]
	v_cndmask_b32_e64 v150, v66, v187, s[0:1]
	v_cmp_gt_i32_e64 s[0:1], s66, v189
	v_cndmask_b32_e32 v50, v187, v50, vcc
	v_cndmask_b32_e32 v151, v67, v187, vcc
	v_cndmask_b32_e64 v51, v187, v51, s[0:1]
	v_cmp_lt_i32_e64 s[0:1], s68, v189
	v_cmp_gt_i32_e32 vcc, s67, v189
	s_nop 0
	v_cndmask_b32_e64 v148, v187, v68, s[0:1]
	v_cmp_gt_i32_e64 s[0:1], s69, v189
	v_cndmask_b32_e32 v52, v187, v52, vcc
	v_cndmask_b32_e32 v149, v69, v187, vcc
	v_cndmask_b32_e64 v53, v187, v53, s[0:1]
	v_cndmask_b32_e64 v90, v70, v187, s[0:1]
	v_cmp_gt_i32_e64 s[0:1], s71, v189
	v_cmp_gt_i32_e32 vcc, s70, v189
	s_nop 0
	v_cndmask_b32_e64 v55, v187, v55, s[0:1]
	v_cmp_lt_i32_e64 s[0:1], s73, v189
	v_cndmask_b32_e32 v54, v187, v54, vcc
	v_cndmask_b32_e32 v91, v71, v187, vcc
	v_cndmask_b32_e64 v72, v187, v72, s[0:1]
	v_cmp_gt_i32_e64 s[0:1], s74, v189
	v_cmp_gt_i32_e32 vcc, s72, v189
	s_nop 0
	v_cndmask_b32_e64 v57, v187, v57, s[0:1]
	v_cndmask_b32_e64 v70, v74, v187, s[0:1]
	v_cmp_gt_i32_e64 s[0:1], s76, v189
	v_cndmask_b32_e32 v56, v187, v56, vcc
	v_cndmask_b32_e32 v73, v73, v187, vcc
	v_cndmask_b32_e64 v59, v187, v59, s[0:1]
	v_cmp_lt_i32_e64 s[0:1], s82, v189
	v_cmp_gt_i32_e32 vcc, s75, v189
	s_nop 0
	v_cndmask_b32_e64 v68, v187, v76, s[0:1]
	v_cmp_gt_i32_e64 s[0:1], s83, v189
	v_cndmask_b32_e32 v58, v187, v58, vcc
	v_cndmask_b32_e32 v71, v75, v187, vcc
	v_cndmask_b32_e64 v61, v187, v61, s[0:1]
	v_cndmask_b32_e64 v66, v78, v187, s[0:1]
	v_cmp_gt_i32_e64 s[0:1], s85, v189
	v_cmp_gt_i32_e32 vcc, s77, v189
	s_nop 0
	v_cndmask_b32_e64 v63, v187, v63, s[0:1]
	s_mov_b32 s0, 0xff800000
	v_max3_f32 v64, v48, s0, v49
	v_max3_f32 v64, v64, v50, v51
	v_max3_f32 v64, v64, v52, v53
	v_max3_f32 v64, v64, v54, v55
	v_max3_f32 v64, v64, v56, v57
	v_cndmask_b32_e32 v60, v187, v60, vcc
	v_cndmask_b32_e32 v69, v77, v187, vcc
	v_cmp_gt_i32_e32 vcc, s84, v189
	v_max3_f32 v64, v64, v58, v59
	v_max3_f32 v64, v64, v60, v61
	v_cndmask_b32_e32 v62, v187, v62, vcc
	v_max3_f32 v64, v64, v62, v63
	v_max3_f32 v64, v64, v32, v33
	v_max3_f32 v64, v64, v34, v35
	v_max3_f32 v64, v64, v36, v37
	v_max3_f32 v64, v64, v38, v39
	v_max3_f32 v64, v64, v40, v41
	v_max3_f32 v64, v64, v42, v43
	v_max3_f32 v64, v64, v44, v45
	v_max3_f32 v64, v64, v46, v47
	v_max3_f32 v64, v64, v16, v17
	v_max3_f32 v64, v64, v18, v19
	v_max3_f32 v64, v64, v20, v21
	v_max3_f32 v64, v64, v22, v23
	v_max3_f32 v64, v64, v24, v25
	v_max3_f32 v64, v64, v26, v27
	v_max3_f32 v64, v64, v28, v29
	v_max3_f32 v64, v64, v30, v31
	v_max3_f32 v64, v64, v0, v1
	v_max3_f32 v64, v64, v2, v3
	v_max3_f32 v64, v64, v4, v5
	v_max3_f32 v64, v64, v6, v7
	v_max3_f32 v64, v64, v8, v9
	v_max3_f32 v64, v64, v10, v11
	v_max3_f32 v64, v64, v12, v13
	v_max3_f32 v64, v64, v14, v15
	v_max3_f32 v64, v64, v152, v153
	v_max3_f32 v64, v64, v150, v151
	v_max3_f32 v64, v64, v148, v149
	v_max3_f32 v64, v64, v90, v91
	v_max3_f32 v64, v64, v72, v73
	v_max3_f32 v64, v64, v70, v71
	v_cndmask_b32_e32 v67, v79, v187, vcc
	v_max3_f32 v64, v64, v68, v69
	v_max3_f32 v64, v64, v66, v67
	v_and_b32_e32 v74, 64, v181
	v_xor_b32_e32 v65, 32, v181
	v_add_u32_e32 v74, 64, v74
	v_cmp_lt_i32_e32 vcc, v65, v74
	s_nop 1
	v_cndmask_b32_e32 v65, v181, v65, vcc
	v_lshlrev_b32_e32 v65, 2, v65
	ds_bpermute_b32 v74, v65, v64
	s_waitcnt lgkmcnt(0)
	v_max_f32_e32 v74, v74, v74
	v_max_f32_e32 v64, v64, v74
	v_add_f32_e64 v48, v48, -v64
	v_add_f32_e64 v49, v49, -v64
	v_add_f32_e64 v50, v50, -v64
	v_add_f32_e64 v51, v51, -v64
	v_exp_f32_e32 v48, v48
	v_exp_f32_e32 v49, v49
	v_exp_f32_e32 v50, v50
	v_exp_f32_e32 v51, v51
	v_add_f32_e64 v52, v52, -v64
	v_add_f32_e64 v53, v53, -v64
	v_add_f32_e64 v54, v54, -v64
	v_add_f32_e64 v55, v55, -v64
	v_exp_f32_e32 v52, v52
	v_exp_f32_e32 v53, v53
	v_exp_f32_e32 v54, v54
	v_exp_f32_e32 v55, v55
	v_add_f32_e64 v56, v56, -v64
	v_add_f32_e64 v57, v57, -v64
	v_add_f32_e64 v74, v48, 0
	v_add_f32_e64 v75, v49, 0
	v_exp_f32_e32 v56, v56
	v_exp_f32_e32 v57, v57
	v_add_f32_e64 v74, v50, v74
	v_add_f32_e64 v75, v51, v75
	v_cvt_pk_bf16_f32 v48, v48, v49
	v_cvt_pk_bf16_f32 v49, v50, v51
	v_cvt_pk_bf16_f32 v50, v52, v53
	v_add_f32_e64 v58, v58, -v64
	v_add_f32_e64 v59, v59, -v64
	v_add_f32_e64 v74, v52, v74
	v_add_f32_e64 v75, v53, v75
	v_exp_f32_e32 v58, v58
	v_add_f32_e64 v52, v54, v74
	v_add_f32_e64 v53, v55, v75
	v_exp_f32_e32 v59, v59
	v_cvt_pk_bf16_f32 v51, v54, v55
	v_add_f32_e64 v54, v56, v52
	v_add_f32_e64 v55, v57, v53
	v_cvt_pk_bf16_f32 v52, v56, v57
	v_add_f32_e64 v56, v60, -v64
	v_add_f32_e64 v57, v61, -v64
	v_add_f32_e64 v60, v62, -v64
	v_add_f32_e64 v61, v63, -v64
	v_exp_f32_e32 v56, v56
	v_exp_f32_e32 v57, v57
	v_exp_f32_e32 v60, v60
	v_exp_f32_e32 v61, v61
	v_add_f32_e64 v54, v58, v54
	v_add_f32_e64 v55, v59, v55
	v_cvt_pk_bf16_f32 v53, v58, v59
	s_nop 0
	v_add_f32_e64 v58, v56, v54
	v_add_f32_e64 v59, v57, v55
	v_cvt_pk_bf16_f32 v54, v56, v57
	v_cvt_pk_bf16_f32 v55, v60, v61
	s_nop 0
	v_add_f32_e64 v56, v60, v58
	v_add_f32_e64 v57, v61, v59
	v_add_f32_e64 v32, v32, -v64
	v_add_f32_e64 v33, v33, -v64
	v_add_f32_e64 v34, v34, -v64
	v_add_f32_e64 v35, v35, -v64
	v_exp_f32_e32 v32, v32
	v_exp_f32_e32 v33, v33
	v_exp_f32_e32 v34, v34
	v_exp_f32_e32 v35, v35
	v_add_f32_e64 v36, v36, -v64
	v_add_f32_e64 v37, v37, -v64
	v_add_f32_e64 v38, v38, -v64
	v_add_f32_e64 v39, v39, -v64
	v_exp_f32_e32 v36, v36
	v_exp_f32_e32 v37, v37
	v_exp_f32_e32 v38, v38
	v_exp_f32_e32 v39, v39
	v_add_f32_e64 v40, v40, -v64
	v_add_f32_e64 v41, v41, -v64
	v_add_f32_e64 v56, v32, v56
	v_add_f32_e64 v57, v33, v57
	v_exp_f32_e32 v40, v40
	v_exp_f32_e32 v41, v41
	v_add_f32_e64 v56, v34, v56
	v_add_f32_e64 v57, v35, v57
	v_cvt_pk_bf16_f32 v32, v32, v33
	v_cvt_pk_bf16_f32 v33, v34, v35
	v_cvt_pk_bf16_f32 v34, v36, v37
	v_add_f32_e64 v42, v42, -v64
	v_add_f32_e64 v43, v43, -v64
	v_add_f32_e64 v56, v36, v56
	v_add_f32_e64 v57, v37, v57
	v_exp_f32_e32 v42, v42
	v_add_f32_e64 v36, v38, v56
	v_add_f32_e64 v37, v39, v57
	v_exp_f32_e32 v43, v43
	v_cvt_pk_bf16_f32 v35, v38, v39
	v_add_f32_e64 v38, v40, v36
	v_add_f32_e64 v39, v41, v37
	v_cvt_pk_bf16_f32 v36, v40, v41
	v_add_f32_e64 v40, v44, -v64
	v_add_f32_e64 v41, v45, -v64
	v_add_f32_e64 v44, v46, -v64
	v_add_f32_e64 v45, v47, -v64
	v_exp_f32_e32 v40, v40
	v_exp_f32_e32 v41, v41
	v_exp_f32_e32 v44, v44
	v_exp_f32_e32 v45, v45
	v_add_f32_e64 v38, v42, v38
	v_add_f32_e64 v39, v43, v39
	v_cvt_pk_bf16_f32 v37, v42, v43
	s_nop 0
	v_add_f32_e64 v42, v40, v38
	v_add_f32_e64 v43, v41, v39
	v_cvt_pk_bf16_f32 v38, v40, v41
	v_cvt_pk_bf16_f32 v39, v44, v45
	s_nop 0
	v_add_f32_e64 v40, v44, v42
	v_add_f32_e64 v41, v45, v43
	v_add_f32_e64 v16, v16, -v64
	v_add_f32_e64 v17, v17, -v64
	v_add_f32_e64 v18, v18, -v64
	v_add_f32_e64 v19, v19, -v64
	v_exp_f32_e32 v16, v16
	v_exp_f32_e32 v17, v17
	v_exp_f32_e32 v18, v18
	v_exp_f32_e32 v19, v19
	v_add_f32_e64 v20, v20, -v64
	v_add_f32_e64 v21, v21, -v64
	v_add_f32_e64 v42, v16, v40
	v_add_f32_e64 v43, v17, v41
	v_exp_f32_e32 v20, v20
	v_exp_f32_e32 v21, v21
	v_add_f32_e64 v22, v22, -v64
	v_add_f32_e64 v23, v23, -v64
	v_cvt_pk_bf16_f32 v40, v16, v17
	v_add_f32_e64 v16, v18, v42
	v_add_f32_e64 v17, v19, v43
	v_exp_f32_e32 v22, v22
	v_exp_f32_e32 v23, v23
	v_cvt_pk_bf16_f32 v41, v18, v19
	v_add_f32_e64 v18, v24, -v64
	v_add_f32_e64 v19, v25, -v64
	v_add_f32_e64 v16, v20, v16
	v_add_f32_e64 v17, v21, v17
	v_exp_f32_e32 v18, v18
	v_exp_f32_e32 v19, v19
	v_cvt_pk_bf16_f32 v42, v20, v21
	v_add_f32_e64 v16, v22, v16
	v_add_f32_e64 v17, v23, v17
	v_add_f32_e64 v20, v26, -v64
	v_add_f32_e64 v21, v27, -v64
	v_cvt_pk_bf16_f32 v43, v22, v23
	v_add_f32_e64 v16, v18, v16
	v_add_f32_e64 v17, v19, v17
	v_exp_f32_e32 v20, v20
	v_exp_f32_e32 v21, v21
	v_cvt_pk_bf16_f32 v44, v18, v19
	v_add_f32_e64 v18, v28, -v64
	v_add_f32_e64 v19, v29, -v64
	v_add_f32_e64 v22, v30, -v64
	v_add_f32_e64 v23, v31, -v64
	v_exp_f32_e32 v18, v18
	v_exp_f32_e32 v19, v19
	v_exp_f32_e32 v22, v22
	v_exp_f32_e32 v23, v23
	v_add_f32_e64 v16, v20, v16
	v_add_f32_e64 v17, v21, v17
	v_cvt_pk_bf16_f32 v45, v20, v21
	v_cvt_pk_bf16_f32 v46, v18, v19
	v_cvt_pk_bf16_f32 v47, v22, v23
	s_nop 0
	v_add_f32_e64 v16, v18, v16
	v_add_f32_e64 v17, v19, v17
	s_nop 0
	v_add_f32_e64 v16, v22, v16
	v_add_f32_e64 v17, v23, v17
	v_add_f32_e64 v0, v0, -v64
	v_add_f32_e64 v1, v1, -v64
	v_add_f32_e64 v2, v2, -v64
	v_add_f32_e64 v3, v3, -v64
	v_exp_f32_e32 v0, v0
	v_exp_f32_e32 v1, v1
	v_exp_f32_e32 v2, v2
	v_exp_f32_e32 v3, v3
	v_add_f32_e64 v4, v4, -v64
	v_add_f32_e64 v5, v5, -v64
	v_add_f32_e64 v16, v0, v16
	v_add_f32_e64 v17, v1, v17
	v_exp_f32_e32 v4, v4
	v_exp_f32_e32 v5, v5
	v_add_f32_e64 v6, v6, -v64
	v_add_f32_e64 v7, v7, -v64
	v_cvt_pk_bf16_f32 v56, v0, v1
	v_add_f32_e64 v0, v2, v16
	v_add_f32_e64 v1, v3, v17
	v_exp_f32_e32 v6, v6
	v_exp_f32_e32 v7, v7
	v_cvt_pk_bf16_f32 v57, v2, v3
	v_add_f32_e64 v2, v8, -v64
	v_add_f32_e64 v3, v9, -v64
	v_add_f32_e64 v0, v4, v0
	v_add_f32_e64 v1, v5, v1
	v_exp_f32_e32 v2, v2
	v_exp_f32_e32 v3, v3
	v_cvt_pk_bf16_f32 v58, v4, v5
	v_add_f32_e64 v0, v6, v0
	v_add_f32_e64 v1, v7, v1
	v_add_f32_e64 v4, v10, -v64
	v_add_f32_e64 v5, v11, -v64
	v_cvt_pk_bf16_f32 v59, v6, v7
	v_add_f32_e64 v0, v2, v0
	v_add_f32_e64 v1, v3, v1
	v_exp_f32_e32 v4, v4
	v_exp_f32_e32 v5, v5
	v_cvt_pk_bf16_f32 v60, v2, v3
	v_add_f32_e64 v2, v12, -v64
	v_add_f32_e64 v3, v13, -v64
	v_add_f32_e64 v6, v14, -v64
	v_add_f32_e64 v7, v15, -v64
	v_exp_f32_e32 v2, v2
	v_exp_f32_e32 v3, v3
	v_exp_f32_e32 v6, v6
	v_exp_f32_e32 v7, v7
	v_add_f32_e64 v0, v4, v0
	v_add_f32_e64 v1, v5, v1
	v_cvt_pk_bf16_f32 v61, v4, v5
	v_cvt_pk_bf16_f32 v62, v2, v3
	v_cvt_pk_bf16_f32 v63, v6, v7
	s_nop 0
	v_add_f32_e64 v0, v2, v0
	v_add_f32_e64 v1, v3, v1
	s_nop 0
	v_add_f32_e64 v0, v6, v0
	v_add_f32_e64 v1, v7, v1
	v_add_f32_e64 v2, v152, -v64
	v_add_f32_e64 v3, v153, -v64
	v_add_f32_e64 v4, v150, -v64
	v_add_f32_e64 v5, v151, -v64
	v_exp_f32_e32 v2, v2
	v_exp_f32_e32 v3, v3
	v_exp_f32_e32 v4, v4
	v_exp_f32_e32 v5, v5
	v_cvt_pk_bf16_f32 v74, v2, v3
	v_add_f32_e64 v0, v2, v0
	v_add_f32_e64 v1, v3, v1
	v_add_f32_e64 v2, v148, -v64
	v_add_f32_e64 v3, v149, -v64
	v_add_f32_e64 v0, v4, v0
	v_add_f32_e64 v1, v5, v1
	v_exp_f32_e32 v2, v2
	v_exp_f32_e32 v3, v3
	v_add_f32_e64 v6, v90, -v64
	v_add_f32_e64 v7, v91, -v64
	v_cvt_pk_bf16_f32 v75, v4, v5
	v_cvt_pk_bf16_f32 v76, v2, v3
	v_add_f32_e64 v0, v2, v0
	v_add_f32_e64 v1, v3, v1
	v_exp_f32_e32 v6, v6
	v_exp_f32_e32 v7, v7
	v_add_f32_e64 v2, v72, -v64
	v_add_f32_e64 v3, v73, -v64
	v_add_f32_e64 v4, v70, -v64
	v_add_f32_e64 v5, v71, -v64
	v_exp_f32_e32 v2, v2
	v_exp_f32_e32 v3, v3
	v_add_f32_e64 v0, v6, v0
	v_add_f32_e64 v1, v7, v1
	v_exp_f32_e32 v4, v4
	v_exp_f32_e32 v5, v5
	v_cvt_pk_bf16_f32 v77, v6, v7
	v_add_f32_e64 v0, v2, v0
	v_add_f32_e64 v1, v3, v1
	v_cvt_pk_bf16_f32 v70, v2, v3
	v_add_f32_e64 v2, v68, -v64
	v_add_f32_e64 v3, v69, -v64
	v_add_f32_e64 v6, v66, -v64
	v_add_f32_e64 v7, v67, -v64
	v_exp_f32_e32 v2, v2
	v_exp_f32_e32 v3, v3
	v_exp_f32_e32 v6, v6
	v_exp_f32_e32 v7, v7
	v_add_f32_e64 v0, v4, v0
	v_add_f32_e64 v1, v5, v1
	v_cvt_pk_bf16_f32 v71, v4, v5
	v_cvt_pk_bf16_f32 v72, v2, v3
	v_cvt_pk_bf16_f32 v73, v6, v7
	s_nop 0
	v_add_f32_e64 v0, v2, v0
	v_add_f32_e64 v1, v3, v1
	s_nop 0
	v_add_f32_e64 v78, v6, v0
	v_add_f32_e64 v79, v7, v1
	ds_read_b64_tr_b16 v[0:1], v169 offset:55296
	ds_read_b64_tr_b16 v[2:3], v169 offset:56448
	ds_read_b64_tr_b16 v[18:19], v169 offset:56512
	ds_read_b64_tr_b16 v[16:17], v169 offset:55360
	s_waitcnt lgkmcnt(2)
	v_mfma_f32_32x32x16_bf16 v[0:15], v[48:51], v[0:3], 0
	s_waitcnt lgkmcnt(0)
	v_mfma_f32_32x32x16_bf16 v[16:31], v[48:51], v[16:19], 0
	ds_read_b64_tr_b16 v[48:49], v169 offset:57600
	ds_read_b64_tr_b16 v[50:51], v169 offset:58752
	ds_read_b64_tr_b16 v[68:69], v169 offset:58816
	ds_read_b64_tr_b16 v[66:67], v169 offset:57664
	s_waitcnt lgkmcnt(2)
	v_mfma_f32_32x32x16_bf16 v[0:15], v[52:55], v[48:51], v[0:15]
	s_waitcnt lgkmcnt(0)
	v_mfma_f32_32x32x16_bf16 v[16:31], v[52:55], v[66:69], v[16:31]
	ds_read_b64_tr_b16 v[48:49], v169 offset:59904
	ds_read_b64_tr_b16 v[50:51], v169 offset:61056
	ds_read_b64_tr_b16 v[54:55], v169 offset:61120
	ds_read_b64_tr_b16 v[52:53], v169 offset:59968
	s_waitcnt lgkmcnt(2)
	v_mfma_f32_32x32x16_bf16 v[0:15], v[32:35], v[48:51], v[0:15]
	s_waitcnt lgkmcnt(0)
	v_mfma_f32_32x32x16_bf16 v[16:31], v[32:35], v[52:55], v[16:31]
	ds_read_b64_tr_b16 v[32:33], v169 offset:62208
	ds_read_b64_tr_b16 v[34:35], v169 offset:63360
	ds_read_b64_tr_b16 v[50:51], v169 offset:63424
	ds_read_b64_tr_b16 v[48:49], v169 offset:62272
	s_waitcnt lgkmcnt(2)
	v_mfma_f32_32x32x16_bf16 v[0:15], v[36:39], v[32:35], v[0:15]
	s_waitcnt lgkmcnt(0)
	v_mfma_f32_32x32x16_bf16 v[16:31], v[36:39], v[48:51], v[16:31]
	ds_read_b64_tr_b16 v[32:33], v169 offset:64512
	ds_read_b64_tr_b16 v[34:35], v170 offset:10368
	ds_read_b64_tr_b16 v[38:39], v170 offset:10432
	ds_read_b64_tr_b16 v[36:37], v169 offset:64576
	s_waitcnt lgkmcnt(2)
	v_mfma_f32_32x32x16_bf16 v[0:15], v[40:43], v[32:35], v[0:15]
	s_waitcnt lgkmcnt(0)
	v_mfma_f32_32x32x16_bf16 v[16:31], v[40:43], v[36:39], v[16:31]
	ds_read_b64_tr_b16 v[32:33], v170 offset:11520
	ds_read_b64_tr_b16 v[34:35], v170 offset:12672
	ds_read_b64_tr_b16 v[38:39], v170 offset:12736
	ds_read_b64_tr_b16 v[36:37], v170 offset:11584
	s_waitcnt lgkmcnt(2)
	v_mfma_f32_32x32x16_bf16 v[0:15], v[44:47], v[32:35], v[0:15]
	s_waitcnt lgkmcnt(0)
	v_mfma_f32_32x32x16_bf16 v[16:31], v[44:47], v[36:39], v[16:31]
	ds_read_b64_tr_b16 v[32:33], v170 offset:13824
	ds_read_b64_tr_b16 v[34:35], v170 offset:14976
	ds_read_b64_tr_b16 v[38:39], v170 offset:15040
	ds_read_b64_tr_b16 v[36:37], v170 offset:13888
	s_waitcnt lgkmcnt(2)
	v_mfma_f32_32x32x16_bf16 v[0:15], v[56:59], v[32:35], v[0:15]
	s_waitcnt lgkmcnt(0)
	v_mfma_f32_32x32x16_bf16 v[16:31], v[56:59], v[36:39], v[16:31]
	ds_read_b64_tr_b16 v[32:33], v170 offset:16128
	ds_read_b64_tr_b16 v[34:35], v170 offset:17280
	ds_read_b64_tr_b16 v[38:39], v170 offset:17344
	ds_read_b64_tr_b16 v[36:37], v170 offset:16192
	s_waitcnt lgkmcnt(2)
	v_mfma_f32_32x32x16_bf16 v[0:15], v[60:63], v[32:35], v[0:15]
	s_waitcnt lgkmcnt(0)
	v_mfma_f32_32x32x16_bf16 v[16:31], v[60:63], v[36:39], v[16:31]
	ds_read_b64_tr_b16 v[32:33], v170 offset:18432
	ds_read_b64_tr_b16 v[34:35], v170 offset:19584
	ds_read_b64_tr_b16 v[38:39], v170 offset:19648
	ds_read_b64_tr_b16 v[36:37], v170 offset:18496
	s_waitcnt lgkmcnt(2)
	v_mfma_f32_32x32x16_bf16 v[0:15], v[74:77], v[32:35], v[0:15]
	s_waitcnt lgkmcnt(0)
	v_mfma_f32_32x32x16_bf16 v[16:31], v[74:77], v[36:39], v[16:31]
	ds_read_b64_tr_b16 v[32:33], v170 offset:20736
	ds_read_b64_tr_b16 v[34:35], v170 offset:21888
	ds_read_b64_tr_b16 v[38:39], v170 offset:21952
	ds_read_b64_tr_b16 v[36:37], v170 offset:20800
	s_waitcnt lgkmcnt(2)
	v_mfma_f32_32x32x16_bf16 v[0:15], v[70:73], v[32:35], v[0:15]
	v_add_f32_e32 v32, v78, v79
	ds_bpermute_b32 v33, v65, v32
	s_waitcnt lgkmcnt(1)
	v_mfma_f32_32x32x16_bf16 v[16:31], v[70:73], v[36:39], v[16:31]
	s_and_saveexec_b64 s[0:1], s[4:5]
	s_cbranch_execz .LBB0_453
	s_waitcnt lgkmcnt(0)
	v_add_f32_e32 v34, v32, v33
	v_div_scale_f32 v36, s[18:19], v34, v34, 1.0
	v_rcp_f32_e32 v37, v36
	v_log_f32_e32 v35, v34
	s_cmp_eq_u32 s64, 0
	s_cselect_b32 s7, s86, 0x1b000000
	v_fma_f32 v38, -v36, v37, 1.0
	v_fmac_f32_e32 v37, v38, v37
	v_div_scale_f32 v38, vcc, 1.0, v34, 1.0
	v_mul_f32_e32 v39, v38, v37
	v_fma_f32 v40, -v36, v39, v38
	v_fmac_f32_e32 v39, v40, v37
	v_fma_f32 v36, -v36, v39, v38
	v_div_fmas_f32 v36, v36, v37, v39
	v_div_fixup_f32 v34, v36, v34, 1.0
	ds_write_b32 v184, v34 offset:4608
	v_rcp_f32_e32 v34, v188
	s_add_u32 s7, s40, s7
	s_addc_u32 s79, s41, 0
	s_lshl_b64 s[18:19], s[16:17], 4
	v_mul_f32_e32 v34, 0x45800000, v34
	s_or_b32 s18, s18, s63
	v_trunc_f32_e32 v34, v34
	s_mul_i32 s19, s19, s60
	s_mul_hi_u32 s95, s18, s60
	v_cvt_u32_f32_e32 v36, v34
	s_add_i32 s95, s95, s19
	s_mul_i32 s18, s18, s60
	s_add_u32 s96, s18, s61
	v_fma_f32 v34, -v34, v188, s87
	s_addc_u32 s95, s95, 0
	v_cmp_ge_f32_e64 s[18:19], |v34|, v188
	v_readfirstlane_b32 s97, v36
	s_cmp_lg_u64 s[18:19], 0
	s_addc_u32 s18, s97, 0
	s_and_b32 s18, s18, 0x1fff
	s_mul_i32 s95, s95, s18
	s_mul_hi_u32 s19, s96, s18
	s_add_i32 s19, s19, s95
	s_mul_i32 s18, s96, s18
	s_lshl_b64 s[18:19], s[18:19], 2
	v_or_b32_e32 v32, s6, v163
	s_add_u32 s18, s7, s18
	v_ashrrev_i32_e32 v33, 31, v32
	s_addc_u32 s19, s79, s19
	v_add_f32_e32 v35, v64, v35
	v_lshl_add_u64 v[32:33], v[32:33], 2, s[18:19]
	global_store_dword v[32:33], v35, off
	s_branch .LBB0_453

.LBB0_522:
	s_or_b64 exec, exec, s[0:1]
	s_nop 15
	s_nop 7
	s_nop 15
	s_nop 7
	v_cvt_pk_bf16_f32 v0, v0, v16
	s_nop 4
	ds_write_b16 v211, v0
	ds_write_b16_d16_hi v211, v0 offset:64
	v_cvt_pk_bf16_f32 v0, v1, v17
	ds_write_b16 v211, v0 offset:144
	ds_write_b16_d16_hi v211, v0 offset:208
	v_cvt_pk_bf16_f32 v0, v2, v18
	ds_write_b16 v211, v0 offset:288
	ds_write_b16_d16_hi v211, v0 offset:352
	v_cvt_pk_bf16_f32 v0, v3, v19
	ds_write_b16 v211, v0 offset:432
	ds_write_b16_d16_hi v211, v0 offset:496
	v_cvt_pk_bf16_f32 v0, v4, v20
	ds_write_b16 v211, v0 offset:1152
	ds_write_b16_d16_hi v211, v0 offset:1216
	v_cvt_pk_bf16_f32 v0, v5, v21
	ds_write_b16 v211, v0 offset:1296
	ds_write_b16_d16_hi v211, v0 offset:1360
	v_cvt_pk_bf16_f32 v0, v6, v22
	ds_write_b16 v211, v0 offset:1440
	ds_write_b16_d16_hi v211, v0 offset:1504
	v_cvt_pk_bf16_f32 v0, v7, v23
	ds_write_b16 v211, v0 offset:1584
	ds_write_b16_d16_hi v211, v0 offset:1648
	v_cvt_pk_bf16_f32 v0, v8, v24
	ds_write_b16 v211, v0 offset:2304
	ds_write_b16_d16_hi v211, v0 offset:2368
	v_cvt_pk_bf16_f32 v0, v9, v25
	ds_write_b16 v211, v0 offset:2448
	ds_write_b16_d16_hi v211, v0 offset:2512
	v_cvt_pk_bf16_f32 v0, v10, v26
	ds_write_b16 v211, v0 offset:2592
	ds_write_b16_d16_hi v211, v0 offset:2656
	v_cvt_pk_bf16_f32 v0, v11, v27
	ds_write_b16 v211, v0 offset:2736
	ds_write_b16_d16_hi v211, v0 offset:2800
	v_cvt_pk_bf16_f32 v0, v12, v28
	ds_write_b16 v211, v0 offset:3456
	ds_write_b16_d16_hi v211, v0 offset:3520
	v_cvt_pk_bf16_f32 v0, v13, v29
	ds_write_b16 v211, v0 offset:3600
	ds_write_b16_d16_hi v211, v0 offset:3664
	v_cvt_pk_bf16_f32 v0, v14, v30
	ds_write_b16 v211, v0 offset:3744
	ds_write_b16_d16_hi v211, v0 offset:3808
	v_cvt_pk_bf16_f32 v0, v15, v31
	ds_write_b16 v211, v0 offset:3888
	ds_write_b16_d16_hi v211, v0 offset:3952
	s_waitcnt lgkmcnt(0)
	v_add_u32_e32 v14, 0x1000, v212
	ds_read_b128 v[2:5], v224
	ds_read2_b32 v[6:7], v14 offset0:128 offset1:160
	ds_read_b32 v12, v212 offset:4864
	s_waitcnt vmcnt(7)
	v_lshlrev_b32_e32 v9, 16, v176
	s_waitcnt vmcnt(6)
	v_lshlrev_b32_e32 v10, 16, v172
	s_waitcnt lgkmcnt(2)
	v_lshlrev_b32_e32 v8, 16, v2
	s_waitcnt lgkmcnt(1)
	v_mul_f32_e64 v8, v6, v8
	v_mul_f32_e64 v9, v7, v9
	v_mov_b32_e32 v11, v6
	s_waitcnt lgkmcnt(0)
	v_fma_f32 v9, v12, v10, v9
	v_add_f32_e32 v13, v8, v9
	v_and_b32_e32 v9, 0xffff0000, v2
	v_and_b32_e32 v8, 0xffff0000, v176
	v_mov_b32_e32 v10, v7
	v_mul_f32_e64 v8, v10, v8
	v_mul_f32_e64 v9, v11, v9
	v_and_b32_e32 v2, 0xffff0000, v172
	v_fma_f32 v2, v12, v2, v8
	v_add_f32_e32 v15, v2, v9
	v_lshlrev_b32_e32 v9, 16, v177
	v_lshlrev_b32_e32 v8, 16, v3
	v_mul_f32_e64 v8, v6, v8
	v_mul_f32_e64 v9, v7, v9
	v_lshlrev_b32_e32 v2, 16, v173
	v_fma_f32 v2, v12, v2, v9
	v_add_f32_e32 v8, v8, v2
	v_and_b32_e32 v3, 0xffff0000, v3
	v_and_b32_e32 v2, 0xffff0000, v177
	v_mul_f32_e64 v2, v10, v2
	v_mul_f32_e64 v3, v11, v3
	v_and_b32_e32 v9, 0xffff0000, v173
	v_fma_f32 v2, v12, v9, v2
	v_add_f32_e32 v9, v2, v3
	v_lshlrev_b32_e32 v3, 16, v178
	v_lshlrev_b32_e32 v2, 16, v4
	v_mul_f32_e64 v2, v6, v2
	v_mul_f32_e64 v3, v7, v3
	v_lshlrev_b32_e32 v16, 16, v174
	v_fma_f32 v3, v12, v16, v3
	v_add_f32_e32 v16, v2, v3
	v_and_b32_e32 v3, 0xffff0000, v4
	v_and_b32_e32 v2, 0xffff0000, v178
	v_mul_f32_e64 v2, v10, v2
	v_mul_f32_e64 v3, v11, v3
	v_and_b32_e32 v4, 0xffff0000, v174
	v_fma_f32 v2, v12, v4, v2
	v_add_f32_e32 v4, v2, v3
	v_lshlrev_b32_e32 v3, 16, v179
	v_lshlrev_b32_e32 v2, 16, v5
	v_mul_f32_e64 v2, v6, v2
	v_mul_f32_e64 v3, v7, v3
	v_lshlrev_b32_e32 v6, 16, v175
	v_fma_f32 v3, v12, v6, v3
	v_add_f32_e32 v6, v2, v3
	v_and_b32_e32 v3, 0xffff0000, v5
	v_and_b32_e32 v2, 0xffff0000, v179
	v_mul_f32_e64 v2, v10, v2
	v_mul_f32_e64 v3, v11, v3
	v_and_b32_e32 v5, 0xffff0000, v175
	v_fma_f32 v2, v12, v5, v2
	v_lshl_add_u64 v[0:1], v[192:193], 0, s[64:65]
	v_add_f32_e32 v5, v2, v3
	v_cvt_pk_bf16_f32 v2, v13, v15
	v_cvt_pk_bf16_f32 v3, v8, v9
	v_cvt_pk_bf16_f32 v4, v16, v4
	v_cvt_pk_bf16_f32 v5, v6, v5
	v_lshl_add_u64 v[10:11], v[0:1], 0, s[62:63]
	ds_read_b128 v[6:9], v224 offset:1152
	ds_read2_b32 v[12:13], v14 offset0:136 offset1:168
	global_store_dwordx4 v[10:11], v[2:5], off
	ds_read_b32 v10, v212 offset:4896
	s_waitcnt vmcnt(5)
	v_lshlrev_b32_e32 v15, 16, v165
	v_lshlrev_b32_e32 v3, 16, v168
	s_waitcnt lgkmcnt(2)
	v_lshlrev_b32_e32 v2, 16, v6
	s_waitcnt lgkmcnt(1)
	v_mul_f32_e64 v2, v12, v2
	v_mul_f32_e64 v3, v13, v3
	v_lshlrev_b32_e32 v4, 16, v164
	s_waitcnt lgkmcnt(0)
	v_fma_f32 v3, v10, v4, v3
	v_add_f32_e32 v11, v2, v3
	v_and_b32_e32 v3, 0xffff0000, v6
	v_and_b32_e32 v2, 0xffff0000, v168
	v_mov_b32_e32 v4, v13
	v_mov_b32_e32 v5, v12
	v_mul_f32_e64 v2, v4, v2
	v_mul_f32_e64 v3, v5, v3
	v_and_b32_e32 v6, 0xffff0000, v164
	v_fma_f32 v2, v10, v6, v2
	v_add_f32_e32 v6, v2, v3
	v_lshlrev_b32_e32 v3, 16, v169
	v_lshlrev_b32_e32 v2, 16, v7
	v_mul_f32_e64 v2, v12, v2
	v_mul_f32_e64 v3, v13, v3
	v_lshlrev_b32_e32 v16, 16, v166
	v_fma_f32 v3, v10, v15, v3
	v_add_f32_e32 v15, v2, v3
	v_and_b32_e32 v3, 0xffff0000, v7
	v_and_b32_e32 v2, 0xffff0000, v169
	v_mul_f32_e64 v2, v4, v2
	v_mul_f32_e64 v3, v5, v3
	v_and_b32_e32 v7, 0xffff0000, v165
	v_fma_f32 v2, v10, v7, v2
	v_add_f32_e32 v7, v2, v3
	v_lshlrev_b32_e32 v3, 16, v170
	v_lshlrev_b32_e32 v2, 16, v8
	v_mul_f32_e64 v2, v12, v2
	v_mul_f32_e64 v3, v13, v3
	s_add_i32 s67, s67, s68
	v_fma_f32 v3, v10, v16, v3
	v_add_f32_e32 v16, v2, v3
	v_and_b32_e32 v3, 0xffff0000, v8
	v_and_b32_e32 v2, 0xffff0000, v170
	v_mul_f32_e64 v2, v4, v2
	v_mul_f32_e64 v3, v5, v3
	v_and_b32_e32 v8, 0xffff0000, v166
	v_fma_f32 v2, v10, v8, v2
	v_add_f32_e32 v8, v2, v3
	v_lshlrev_b32_e32 v3, 16, v171
	v_lshlrev_b32_e32 v2, 16, v9
	v_mul_f32_e64 v2, v12, v2
	v_mul_f32_e64 v3, v13, v3
	v_lshlrev_b32_e32 v12, 16, v167
	v_fma_f32 v3, v10, v12, v3
	v_add_f32_e32 v12, v2, v3
	v_and_b32_e32 v3, 0xffff0000, v9
	v_and_b32_e32 v2, 0xffff0000, v171
	v_mul_f32_e64 v2, v4, v2
	v_mul_f32_e64 v3, v5, v3
	v_and_b32_e32 v4, 0xffff0000, v167
	v_fma_f32 v2, v10, v4, v2
	v_add_f32_e32 v5, v2, v3
	v_cvt_pk_bf16_f32 v2, v11, v6
	v_cvt_pk_bf16_f32 v3, v15, v7
	v_cvt_pk_bf16_f32 v4, v16, v8
	v_cvt_pk_bf16_f32 v5, v12, v5
	v_lshl_add_u64 v[10:11], v[0:1], 0, s[60:61]
	ds_read_b128 v[6:9], v224 offset:2304
	ds_read2_b32 v[12:13], v14 offset0:144 offset1:176
	global_store_dwordx4 v[10:11], v[2:5], off
	ds_read_b32 v10, v212 offset:4928
	s_waitcnt vmcnt(4)
	v_lshlrev_b32_e32 v15, 16, v157
	v_lshlrev_b32_e32 v3, 16, v160
	s_waitcnt lgkmcnt(2)
	v_lshlrev_b32_e32 v2, 16, v6
	s_waitcnt lgkmcnt(1)
	v_mul_f32_e64 v2, v12, v2
	v_mul_f32_e64 v3, v13, v3
	v_lshlrev_b32_e32 v4, 16, v156
	s_waitcnt lgkmcnt(0)
	v_fma_f32 v3, v10, v4, v3
	v_add_f32_e32 v11, v2, v3
	v_and_b32_e32 v3, 0xffff0000, v6
	v_and_b32_e32 v2, 0xffff0000, v160
	v_mov_b32_e32 v4, v13
	v_mov_b32_e32 v5, v12
	v_mul_f32_e64 v2, v4, v2
	v_mul_f32_e64 v3, v5, v3
	v_and_b32_e32 v6, 0xffff0000, v156
	v_fma_f32 v2, v10, v6, v2
	v_add_f32_e32 v6, v2, v3
	v_lshlrev_b32_e32 v3, 16, v161
	v_lshlrev_b32_e32 v2, 16, v7
	v_mul_f32_e64 v2, v12, v2
	v_mul_f32_e64 v3, v13, v3
	v_lshlrev_b32_e32 v16, 16, v158
	v_fma_f32 v3, v10, v15, v3
	v_add_f32_e32 v15, v2, v3
	v_and_b32_e32 v3, 0xffff0000, v7
	v_and_b32_e32 v2, 0xffff0000, v161
	v_mul_f32_e64 v2, v4, v2
	v_mul_f32_e64 v3, v5, v3
	v_and_b32_e32 v7, 0xffff0000, v157
	v_fma_f32 v2, v10, v7, v2
	v_add_f32_e32 v7, v2, v3
	v_lshlrev_b32_e32 v3, 16, v162
	v_lshlrev_b32_e32 v2, 16, v8
	v_mul_f32_e64 v2, v12, v2
	v_mul_f32_e64 v3, v13, v3
	s_andn2_b64 vcc, exec, s[56:57]
	v_fma_f32 v3, v10, v16, v3
	v_add_f32_e32 v16, v2, v3
	v_and_b32_e32 v3, 0xffff0000, v8
	v_and_b32_e32 v2, 0xffff0000, v162
	v_mul_f32_e64 v2, v4, v2
	v_mul_f32_e64 v3, v5, v3
	v_and_b32_e32 v8, 0xffff0000, v158
	v_fma_f32 v2, v10, v8, v2
	v_add_f32_e32 v8, v2, v3
	v_lshlrev_b32_e32 v3, 16, v163
	v_lshlrev_b32_e32 v2, 16, v9
	v_mul_f32_e64 v2, v12, v2
	v_mul_f32_e64 v3, v13, v3
	v_lshlrev_b32_e32 v12, 16, v159
	v_fma_f32 v3, v10, v12, v3
	v_add_f32_e32 v12, v2, v3
	v_and_b32_e32 v3, 0xffff0000, v9
	v_and_b32_e32 v2, 0xffff0000, v163
	v_mul_f32_e64 v2, v4, v2
	v_mul_f32_e64 v3, v5, v3
	v_and_b32_e32 v4, 0xffff0000, v159
	v_fma_f32 v2, v10, v4, v2
	v_add_f32_e32 v5, v2, v3
	v_cvt_pk_bf16_f32 v2, v11, v6
	v_cvt_pk_bf16_f32 v3, v15, v7
	v_cvt_pk_bf16_f32 v4, v16, v8
	v_cvt_pk_bf16_f32 v5, v12, v5
	v_lshl_add_u64 v[10:11], v[0:1], 0, s[58:59]
	ds_read_b128 v[6:9], v224 offset:3456
	ds_read2_b32 v[12:13], v14 offset0:152 offset1:184
	global_store_dwordx4 v[10:11], v[2:5], off
	ds_read_b32 v10, v212 offset:4960
	s_waitcnt vmcnt(3)
	v_lshlrev_b32_e32 v14, 16, v149
	v_lshlrev_b32_e32 v3, 16, v152
	s_waitcnt lgkmcnt(2)
	v_lshlrev_b32_e32 v2, 16, v6
	s_waitcnt lgkmcnt(1)
	v_mul_f32_e64 v2, v12, v2
	v_mul_f32_e64 v3, v13, v3
	v_lshlrev_b32_e32 v4, 16, v148
	s_waitcnt lgkmcnt(0)
	v_fma_f32 v3, v10, v4, v3
	v_add_f32_e32 v11, v2, v3
	v_and_b32_e32 v3, 0xffff0000, v6
	v_and_b32_e32 v2, 0xffff0000, v152
	v_mov_b32_e32 v4, v13
	v_mov_b32_e32 v5, v12
	v_mul_f32_e64 v2, v4, v2
	v_mul_f32_e64 v3, v5, v3
	v_and_b32_e32 v6, 0xffff0000, v148
	v_fma_f32 v2, v10, v6, v2
	v_add_f32_e32 v6, v2, v3
	v_lshlrev_b32_e32 v3, 16, v153
	v_lshlrev_b32_e32 v2, 16, v7
	v_mul_f32_e64 v2, v12, v2
	v_mul_f32_e64 v3, v13, v3
	v_lshlrev_b32_e32 v15, 16, v150
	v_fma_f32 v3, v10, v14, v3
	v_add_f32_e32 v14, v2, v3
	v_and_b32_e32 v3, 0xffff0000, v7
	v_and_b32_e32 v2, 0xffff0000, v153
	v_mul_f32_e64 v2, v4, v2
	v_mul_f32_e64 v3, v5, v3
	v_and_b32_e32 v7, 0xffff0000, v149
	v_fma_f32 v2, v10, v7, v2
	v_add_f32_e32 v7, v2, v3
	v_lshlrev_b32_e32 v3, 16, v154
	v_lshlrev_b32_e32 v2, 16, v8
	v_mul_f32_e64 v2, v12, v2
	v_mul_f32_e64 v3, v13, v3
	v_lshl_add_u64 v[0:1], v[0:1], 0, s[6:7]
	v_fma_f32 v3, v10, v15, v3
	v_add_f32_e32 v15, v2, v3
	v_and_b32_e32 v3, 0xffff0000, v8
	v_and_b32_e32 v2, 0xffff0000, v154
	v_mul_f32_e64 v2, v4, v2
	v_mul_f32_e64 v3, v5, v3
	v_and_b32_e32 v8, 0xffff0000, v150
	v_fma_f32 v2, v10, v8, v2
	v_add_f32_e32 v8, v2, v3
	v_lshlrev_b32_e32 v3, 16, v155
	v_lshlrev_b32_e32 v2, 16, v9
	v_mul_f32_e64 v2, v12, v2
	v_mul_f32_e64 v3, v13, v3
	v_lshlrev_b32_e32 v12, 16, v151
	v_fma_f32 v3, v10, v12, v3
	v_add_f32_e32 v12, v2, v3
	v_and_b32_e32 v3, 0xffff0000, v9
	v_and_b32_e32 v2, 0xffff0000, v155
	v_mul_f32_e64 v2, v4, v2
	v_mul_f32_e64 v3, v5, v3
	v_and_b32_e32 v4, 0xffff0000, v151
	v_fma_f32 v2, v10, v4, v2
	v_add_f32_e32 v5, v2, v3
	s_mov_b32 s63, s96
	s_mov_b32 s62, s97
	s_mov_b32 s0, s54
	v_cvt_pk_bf16_f32 v2, v11, v6
	v_cvt_pk_bf16_f32 v3, v14, v7
	v_cvt_pk_bf16_f32 v4, v15, v8
	v_cvt_pk_bf16_f32 v5, v12, v5
	global_store_dwordx4 v[0:1], v[2:5], off
	s_barrier
	s_cbranch_vccz .LBB0_532

.LBB0_530:
	s_waitcnt lgkmcnt(0)
	s_barrier
	v_cndmask_b32_e64 v0, 0, v225, s[6:7]
	v_fmac_f32_e32 v0, -0.5, v4
	v_exp_f32_e32 v0, v0
	s_add_i32 s6, s63, s66
	s_lshl_b32 s7, s62, 7
	v_or_b32_e32 v89, s6, v181
	v_ldexp_f32 v0, v0, s1
	s_ashr_i32 s1, s0, 31
	v_mul_f32_e32 v72, 0x3fb8aa3b, v0
	v_add_u32_e32 v0, v205, v206
	v_mov_b32_e32 v228, v207
	ds_read_b128 v[160:163], v0
	ds_read_b128 v[156:159], v0 offset:32
	ds_read_b128 v[152:155], v0 offset:64
	ds_read_b128 v[148:151], v0 offset:96
	s_cmpk_gt_i32 s6, 0x7f
	v_cvt_f32_i32_e32 v0, v228
	v_mul_f32_e32 v9, 0, v72
	s_cselect_b64 vcc, -1, 0
	v_cndmask_b32_e32 v10, v226, v9, vcc
	v_mul_f32_e64 v8, -v72, v0
	v_fma_f32 v91, -v72, v0, v72
	ds_read_b128 v[0:3], v217
	ds_read_b128 v[4:7], v217 offset:32
	v_fma_f32 v90, 0, v72, v8
	v_fma_f32 v172, v72, s8, v8
	v_fma_f32 v173, v72, s9, v8
	v_fma_f32 v174, v72, s10, v8
	v_fma_f32 v175, v72, s11, v8
	v_fma_f32 v176, v72, s36, v8
	v_fma_f32 v177, v72, s37, v8
	v_fma_f32 v178, v72, s44, v8
	v_fma_f32 v179, v72, s45, v8
	v_fma_f32 v74, v72, s46, v8
	v_fma_f32 v75, v72, s47, v8
	v_fma_f32 v76, v72, s48, v8
	v_fma_f32 v77, v72, s49, v8
	v_fma_f32 v78, v72, s52, v8
	v_fma_f32 v79, v72, s53, v8
	v_add_f32_e64 v62, v10, v78
	v_add_f32_e64 v63, v10, v79
	v_add_f32_e64 v60, v10, v76
	v_add_f32_e64 v61, v10, v77
	v_add_f32_e64 v58, v10, v74
	v_add_f32_e64 v59, v10, v75
	v_add_f32_e64 v56, v10, v178
	v_add_f32_e64 v57, v10, v179
	v_add_f32_e64 v54, v10, v176
	v_add_f32_e64 v55, v10, v177
	v_add_f32_e64 v52, v10, v174
	v_add_f32_e64 v53, v10, v175
	v_add_f32_e64 v50, v10, v172
	v_add_f32_e64 v51, v10, v173
	v_add_f32_e64 v48, v10, v90
	v_add_f32_e64 v49, v10, v91
	s_cmpk_gt_i32 s6, 0x5f
	v_mul_f32_e32 v12, 0x42000000, v72
	s_waitcnt lgkmcnt(1)
	v_mfma_f32_32x32x16_bf16 v[48:63], v[0:3], v[160:163], v[48:63]
	s_cselect_b64 vcc, -1, 0
	v_cndmask_b32_e32 v12, v226, v12, vcc
	v_add_f32_e64 v46, v12, v78
	v_add_f32_e64 v47, v12, v79
	v_add_f32_e64 v44, v12, v76
	v_add_f32_e64 v45, v12, v77
	v_add_f32_e64 v42, v12, v74
	v_add_f32_e64 v43, v12, v75
	v_add_f32_e64 v40, v12, v178
	v_add_f32_e64 v41, v12, v179
	v_add_f32_e64 v38, v12, v176
	v_add_f32_e64 v39, v12, v177
	s_waitcnt lgkmcnt(0)
	v_mfma_f32_32x32x16_bf16 v[48:63], v[4:7], v[156:159], v[48:63]
	ds_read_b128 v[0:3], v217 offset:64
	ds_read_b128 v[4:7], v217 offset:96
	v_add_f32_e64 v36, v12, v174
	v_add_f32_e64 v37, v12, v175
	v_add_f32_e64 v34, v12, v172
	v_add_f32_e64 v35, v12, v173
	v_add_f32_e64 v32, v12, v90
	v_add_f32_e64 v33, v12, v91
	s_cmp_gt_i32 s6, 63
	v_mul_f32_e32 v12, 0x42800000, v72
	s_cselect_b64 vcc, -1, 0
	s_waitcnt lgkmcnt(1)
	v_mfma_f32_32x32x16_bf16 v[48:63], v[0:3], v[152:155], v[48:63]
	ds_read_b128 v[0:3], v218
	ds_read_b128 v[8:11], v218 offset:32
	v_cndmask_b32_e32 v12, v226, v12, vcc
	v_add_f32_e64 v30, v12, v78
	v_add_f32_e64 v31, v12, v79
	v_add_f32_e64 v28, v12, v76
	v_add_f32_e64 v29, v12, v77
	v_add_f32_e64 v26, v12, v74
	v_add_f32_e64 v27, v12, v75
	v_add_f32_e64 v24, v12, v178
	v_add_f32_e64 v25, v12, v179
	v_add_f32_e64 v22, v12, v176
	v_add_f32_e64 v23, v12, v177
	s_waitcnt lgkmcnt(1)
	v_mfma_f32_32x32x16_bf16 v[32:47], v[0:3], v[160:163], v[32:47]
	v_add_f32_e64 v20, v12, v174
	v_add_f32_e64 v21, v12, v175
	v_add_f32_e64 v18, v12, v172
	v_add_f32_e64 v19, v12, v173
	v_add_f32_e64 v16, v12, v90
	v_add_f32_e64 v17, v12, v91
	s_cmp_gt_i32 s6, 31
	s_cselect_b64 vcc, -1, 0
	s_cmp_gt_i32 s6, -1
	s_waitcnt lgkmcnt(0)
	v_mfma_f32_32x32x16_bf16 v[32:47], v[8:11], v[156:159], v[32:47]
	v_mfma_f32_32x32x16_bf16 v[48:63], v[4:7], v[148:151], v[48:63]
	ds_read_b128 v[0:3], v218 offset:64
	ds_read_b128 v[4:7], v218 offset:96
	s_waitcnt lgkmcnt(1)
	v_mfma_f32_32x32x16_bf16 v[32:47], v[0:3], v[152:155], v[32:47]
	ds_read_b128 v[0:3], v219
	ds_read_b128 v[8:11], v219 offset:32
	s_waitcnt lgkmcnt(1)
	v_mfma_f32_32x32x16_bf16 v[16:31], v[0:3], v[160:163], v[16:31]
	s_waitcnt lgkmcnt(0)
	v_mfma_f32_32x32x16_bf16 v[16:31], v[8:11], v[156:159], v[16:31]
	v_mfma_f32_32x32x16_bf16 v[32:47], v[4:7], v[148:151], v[32:47]
	ds_read_b128 v[0:3], v219 offset:64
	ds_read_b128 v[4:7], v219 offset:96
	ds_read_b128 v[64:67], v220
	ds_read_b128 v[68:71], v220 offset:32
	s_waitcnt lgkmcnt(3)
	v_mfma_f32_32x32x16_bf16 v[16:31], v[0:3], v[152:155], v[16:31]
	v_mul_f32_e32 v0, 0x42c00000, v72
	v_cndmask_b32_e32 v0, v226, v0, vcc
	v_add_f32_e64 v14, v0, v78
	v_add_f32_e64 v15, v0, v79
	v_add_f32_e64 v12, v0, v76
	v_add_f32_e64 v13, v0, v77
	v_add_f32_e64 v10, v0, v74
	v_add_f32_e64 v11, v0, v75
	v_add_f32_e64 v8, v0, v178
	v_add_f32_e64 v9, v0, v179
	v_add_f32_e64 v2, v0, v172
	v_add_f32_e64 v3, v0, v173
	s_waitcnt lgkmcnt(2)
	v_mfma_f32_32x32x16_bf16 v[16:31], v[4:7], v[148:151], v[16:31]
	v_add_f32_e64 v6, v0, v176
	v_add_f32_e64 v7, v0, v177
	v_add_f32_e64 v4, v0, v174
	v_add_f32_e64 v5, v0, v175
	v_add_f32_e64 v1, v0, v91
	v_add_f32_e64 v0, v0, v90
	s_cselect_b64 vcc, -1, 0
	s_waitcnt lgkmcnt(1)
	v_mfma_f32_32x32x16_bf16 v[0:15], v[64:67], v[160:163], v[0:15]
	s_waitcnt lgkmcnt(0)
	v_mfma_f32_32x32x16_bf16 v[0:15], v[68:71], v[156:159], v[0:15]
	ds_read_b128 v[64:67], v220 offset:64
	ds_read_b128 v[68:71], v220 offset:96
	ds_read_b128 v[164:167], v221
	ds_read_b128 v[168:171], v221 offset:32
	s_waitcnt lgkmcnt(3)
	v_mfma_f32_32x32x16_bf16 v[0:15], v[64:67], v[152:155], v[0:15]
	v_mul_f32_e32 v64, 0x43000000, v72
	v_cndmask_b32_e32 v64, v226, v64, vcc
	v_add_f32_e64 v78, v64, v78
	v_add_f32_e64 v79, v64, v79
	v_add_f32_e64 v76, v64, v76
	v_add_f32_e64 v77, v64, v77
	v_add_f32_e64 v74, v64, v74
	v_add_f32_e64 v75, v64, v75
	v_add_f32_e64 v72, v64, v178
	v_add_f32_e64 v73, v64, v179
	v_add_f32_e64 v66, v64, v172
	v_add_f32_e64 v67, v64, v173
	s_waitcnt lgkmcnt(2)
	v_mfma_f32_32x32x16_bf16 v[0:15], v[68:71], v[148:151], v[0:15]
	v_add_f32_e64 v70, v64, v176
	v_add_f32_e64 v71, v64, v177
	v_add_f32_e64 v68, v64, v174
	v_add_f32_e64 v69, v64, v175
	v_add_f32_e64 v65, v64, v91
	v_add_f32_e64 v64, v64, v90
	s_waitcnt lgkmcnt(1)
	s_nop 0
	v_mfma_f32_32x32x16_bf16 v[64:79], v[164:167], v[160:163], v[64:79]
	s_waitcnt lgkmcnt(0)
	v_mfma_f32_32x32x16_bf16 v[64:79], v[168:171], v[156:159], v[64:79]
	ds_read_b128 v[156:159], v221 offset:64
	ds_read_b128 v[160:163], v221 offset:96
	s_waitcnt lgkmcnt(1)
	v_mfma_f32_32x32x16_bf16 v[64:79], v[156:159], v[152:155], v[64:79]
	s_waitcnt lgkmcnt(0)
	v_mfma_f32_32x32x16_bf16 v[64:79], v[160:163], v[148:151], v[64:79]
	s_lshl_b64 s[18:19], s[0:1], 18
	s_lshl_b32 s16, s62, 14
	s_lshl_b64 s[64:65], s[0:1], 23
	v_ashrrev_i32_e32 v90, 2, v89
	s_or_b32 s18, s18, s16
	s_or_b32 s64, s64, s7
	s_ashr_i32 s7, s6, 31
	v_ashrrev_i32_e32 v91, 31, v90
	v_lshl_add_u64 v[148:149], v[194:195], 0, s[18:19]
	s_lshl_b64 s[62:63], s[6:7], 11
	v_lshl_add_u64 v[90:91], v[90:91], 2, v[148:149]
	v_ashrrev_i32_e32 v148, 4, v89
	s_add_u32 s0, s64, s62
	v_ashrrev_i32_e32 v149, 31, v148
	v_lshl_add_u64 v[150:151], v[196:197], 0, s[18:19]
	s_addc_u32 s1, s65, s63
	v_lshl_add_u64 v[148:149], v[148:149], 2, v[150:151]
	v_lshl_add_u64 v[150:151], v[190:191], 0, s[0:1]
	global_load_dword v227, v[90:91], off
	global_load_dword v89, v[148:149], off
	global_load_dwordx4 v[176:179], v[150:151], off
	v_lshl_add_u64 v[90:91], v[192:193], 0, s[0:1]
	s_or_b32 s0, s6, 8
	s_ashr_i32 s1, s0, 31
	s_lshl_b64 s[60:61], s[0:1], 11
	s_add_u32 s0, s64, s60
	s_addc_u32 s1, s65, s61
	global_load_dwordx4 v[172:175], v[90:91], off
	v_lshl_add_u64 v[90:91], v[190:191], 0, s[0:1]
	global_load_dwordx4 v[168:171], v[90:91], off
	v_lshl_add_u64 v[90:91], v[192:193], 0, s[0:1]
	s_or_b32 s0, s6, 16
	s_ashr_i32 s1, s0, 31
	s_lshl_b64 s[58:59], s[0:1], 11
	s_add_u32 s0, s64, s58
	s_addc_u32 s1, s65, s59
	global_load_dwordx4 v[164:167], v[90:91], off
	v_lshl_add_u64 v[90:91], v[190:191], 0, s[0:1]
	global_load_dwordx4 v[160:163], v[90:91], off
	v_lshl_add_u64 v[90:91], v[192:193], 0, s[0:1]
	s_or_b32 s0, s6, 24
	s_ashr_i32 s1, s0, 31
	s_lshl_b64 s[6:7], s[0:1], 11
	s_add_u32 s0, s64, s6
	s_addc_u32 s1, s65, s7
	global_load_dwordx4 v[156:159], v[90:91], off
	v_lshl_add_u64 v[90:91], v[190:191], 0, s[0:1]
	global_load_dwordx4 v[152:155], v[90:91], off
	v_lshl_add_u64 v[90:91], v[192:193], 0, s[0:1]
	global_load_dwordx4 v[148:151], v[90:91], off
	v_cmp_lt_i32_e64 s[0:1], s70, v228
	v_cmp_gt_i32_e32 vcc, s72, v228
	s_nop 0
	v_cndmask_b32_e64 v202, v226, v64, s[0:1]
	v_cmp_gt_i32_e64 s[0:1], s73, v228
	v_cndmask_b32_e32 v48, v226, v48, vcc
	v_cndmask_b32_e32 v203, v65, v226, vcc
	v_cndmask_b32_e64 v49, v226, v49, s[0:1]
	v_cndmask_b32_e64 v200, v66, v226, s[0:1]
	v_cmp_gt_i32_e64 s[0:1], s75, v228
	v_cmp_gt_i32_e32 vcc, s74, v228
	v_max3_f32 v64, v48, s71, v49
	v_cndmask_b32_e64 v51, v226, v51, s[0:1]
	v_cmp_lt_i32_e64 s[0:1], s77, v228
	v_cndmask_b32_e32 v50, v226, v50, vcc
	v_cndmask_b32_e32 v201, v67, v226, vcc
	v_cndmask_b32_e64 v198, v226, v68, s[0:1]
	v_cmp_gt_i32_e64 s[0:1], s82, v228
	v_cmp_gt_i32_e32 vcc, s76, v228
	v_max3_f32 v64, v64, v50, v51
	v_cndmask_b32_e64 v53, v226, v53, s[0:1]
	v_cndmask_b32_e64 v90, v70, v226, s[0:1]
	v_cmp_gt_i32_e64 s[0:1], s84, v228
	v_cndmask_b32_e32 v52, v226, v52, vcc
	v_cndmask_b32_e32 v199, v69, v226, vcc
	v_cndmask_b32_e64 v55, v226, v55, s[0:1]
	v_cmp_lt_i32_e64 s[0:1], s86, v228
	v_cmp_gt_i32_e32 vcc, s83, v228
	v_max3_f32 v64, v64, v52, v53
	v_cndmask_b32_e64 v72, v226, v72, s[0:1]
	v_cmp_gt_i32_e64 s[0:1], s87, v228
	v_cndmask_b32_e32 v54, v226, v54, vcc
	v_cndmask_b32_e32 v91, v71, v226, vcc
	v_cmp_gt_i32_e32 vcc, s85, v228
	v_cndmask_b32_e64 v57, v226, v57, s[0:1]
	v_cndmask_b32_e64 v70, v74, v226, s[0:1]
	v_cmp_gt_i32_e64 s[0:1], s89, v228
	v_cndmask_b32_e32 v56, v226, v56, vcc
	v_cndmask_b32_e32 v73, v73, v226, vcc
	v_cmp_gt_i32_e32 vcc, s88, v228
	v_cndmask_b32_e64 v59, v226, v59, s[0:1]
	v_cmp_lt_i32_e64 s[0:1], s91, v228
	v_max3_f32 v64, v64, v54, v55
	v_cndmask_b32_e32 v58, v226, v58, vcc
	v_cndmask_b32_e32 v71, v75, v226, vcc
	v_cmp_gt_i32_e32 vcc, s90, v228
	v_cndmask_b32_e64 v68, v226, v76, s[0:1]
	v_cmp_gt_i32_e64 s[0:1], s92, v228
	v_max3_f32 v64, v64, v56, v57
	v_cndmask_b32_e32 v60, v226, v60, vcc
	v_cndmask_b32_e64 v61, v226, v61, s[0:1]
	v_cndmask_b32_e32 v69, v77, v226, vcc
	v_cmp_gt_i32_e32 vcc, s93, v228
	v_cndmask_b32_e64 v66, v78, v226, s[0:1]
	v_cmp_gt_i32_e64 s[0:1], s94, v228
	v_max3_f32 v64, v64, v58, v59
	v_cndmask_b32_e32 v62, v226, v62, vcc
	v_cndmask_b32_e64 v63, v226, v63, s[0:1]
	v_max3_f32 v64, v64, v60, v61
	v_max3_f32 v64, v64, v62, v63
	v_max3_f32 v64, v64, v32, v33
	v_max3_f32 v64, v64, v34, v35
	v_max3_f32 v64, v64, v36, v37
	v_max3_f32 v64, v64, v38, v39
	v_max3_f32 v64, v64, v40, v41
	v_max3_f32 v64, v64, v42, v43
	v_max3_f32 v64, v64, v44, v45
	v_max3_f32 v64, v64, v46, v47
	v_max3_f32 v64, v64, v16, v17
	v_max3_f32 v64, v64, v18, v19
	v_max3_f32 v64, v64, v20, v21
	v_max3_f32 v64, v64, v22, v23
	v_max3_f32 v64, v64, v24, v25
	v_max3_f32 v64, v64, v26, v27
	v_max3_f32 v64, v64, v28, v29
	v_max3_f32 v64, v64, v30, v31
	v_max3_f32 v64, v64, v0, v1
	v_max3_f32 v64, v64, v2, v3
	v_max3_f32 v64, v64, v4, v5
	v_max3_f32 v64, v64, v6, v7
	v_max3_f32 v64, v64, v8, v9
	v_max3_f32 v64, v64, v10, v11
	v_max3_f32 v64, v64, v12, v13
	v_max3_f32 v64, v64, v14, v15
	v_max3_f32 v64, v64, v202, v203
	v_max3_f32 v64, v64, v200, v201
	v_max3_f32 v64, v64, v198, v199
	v_max3_f32 v64, v64, v90, v91
	v_max3_f32 v64, v64, v72, v73
	v_max3_f32 v64, v64, v70, v71
	v_cndmask_b32_e32 v67, v79, v226, vcc
	v_max3_f32 v64, v64, v68, v69
	v_max3_f32 v64, v64, v66, v67
	v_and_b32_e32 v74, 64, v222
	v_xor_b32_e32 v65, 32, v222
	v_add_u32_e32 v74, 64, v74
	v_cmp_lt_i32_e32 vcc, v65, v74
	s_nop 1
	v_cndmask_b32_e32 v65, v222, v65, vcc
	v_lshlrev_b32_e32 v65, 2, v65
	ds_bpermute_b32 v74, v65, v64
	s_waitcnt lgkmcnt(0)
	v_max_f32_e32 v74, v74, v74
	v_max_f32_e32 v64, v64, v74
	v_add_f32_e64 v48, v48, -v64
	v_add_f32_e64 v49, v49, -v64
	v_add_f32_e64 v50, v50, -v64
	v_add_f32_e64 v51, v51, -v64
	v_exp_f32_e32 v48, v48
	v_exp_f32_e32 v49, v49
	v_exp_f32_e32 v50, v50
	v_exp_f32_e32 v51, v51
	v_add_f32_e64 v52, v52, -v64
	v_add_f32_e64 v53, v53, -v64
	v_add_f32_e64 v54, v54, -v64
	v_add_f32_e64 v55, v55, -v64
	v_exp_f32_e32 v52, v52
	v_exp_f32_e32 v53, v53
	v_exp_f32_e32 v54, v54
	v_exp_f32_e32 v55, v55
	v_add_f32_e64 v56, v56, -v64
	v_add_f32_e64 v57, v57, -v64
	v_add_f32_e64 v74, v48, 0
	v_add_f32_e64 v75, v49, 0
	v_exp_f32_e32 v56, v56
	v_exp_f32_e32 v57, v57
	v_add_f32_e64 v74, v50, v74
	v_add_f32_e64 v75, v51, v75
	v_cvt_pk_bf16_f32 v48, v48, v49
	v_cvt_pk_bf16_f32 v49, v50, v51
	v_cvt_pk_bf16_f32 v50, v52, v53
	v_add_f32_e64 v58, v58, -v64
	v_add_f32_e64 v59, v59, -v64
	v_add_f32_e64 v74, v52, v74
	v_add_f32_e64 v75, v53, v75
	v_exp_f32_e32 v58, v58
	v_add_f32_e64 v52, v54, v74
	v_add_f32_e64 v53, v55, v75
	v_exp_f32_e32 v59, v59
	v_cvt_pk_bf16_f32 v51, v54, v55
	v_add_f32_e64 v54, v56, v52
	v_add_f32_e64 v55, v57, v53
	v_cvt_pk_bf16_f32 v52, v56, v57
	v_add_f32_e64 v56, v60, -v64
	v_add_f32_e64 v57, v61, -v64
	v_add_f32_e64 v60, v62, -v64
	v_add_f32_e64 v61, v63, -v64
	v_exp_f32_e32 v56, v56
	v_exp_f32_e32 v57, v57
	v_exp_f32_e32 v60, v60
	v_exp_f32_e32 v61, v61
	v_add_f32_e64 v54, v58, v54
	v_add_f32_e64 v55, v59, v55
	v_cvt_pk_bf16_f32 v53, v58, v59
	s_nop 0
	v_add_f32_e64 v58, v56, v54
	v_add_f32_e64 v59, v57, v55
	v_cvt_pk_bf16_f32 v54, v56, v57
	v_cvt_pk_bf16_f32 v55, v60, v61
	s_nop 0
	v_add_f32_e64 v56, v60, v58
	v_add_f32_e64 v57, v61, v59
	v_add_f32_e64 v32, v32, -v64
	v_add_f32_e64 v33, v33, -v64
	v_add_f32_e64 v34, v34, -v64
	v_add_f32_e64 v35, v35, -v64
	v_exp_f32_e32 v32, v32
	v_exp_f32_e32 v33, v33
	v_exp_f32_e32 v34, v34
	v_exp_f32_e32 v35, v35
	v_add_f32_e64 v36, v36, -v64
	v_add_f32_e64 v37, v37, -v64
	v_add_f32_e64 v38, v38, -v64
	v_add_f32_e64 v39, v39, -v64
	v_exp_f32_e32 v36, v36
	v_exp_f32_e32 v37, v37
	v_exp_f32_e32 v38, v38
	v_exp_f32_e32 v39, v39
	v_add_f32_e64 v40, v40, -v64
	v_add_f32_e64 v41, v41, -v64
	v_add_f32_e64 v56, v32, v56
	v_add_f32_e64 v57, v33, v57
	v_exp_f32_e32 v40, v40
	v_exp_f32_e32 v41, v41
	v_add_f32_e64 v56, v34, v56
	v_add_f32_e64 v57, v35, v57
	v_cvt_pk_bf16_f32 v32, v32, v33
	v_cvt_pk_bf16_f32 v33, v34, v35
	v_cvt_pk_bf16_f32 v34, v36, v37
	v_add_f32_e64 v42, v42, -v64
	v_add_f32_e64 v43, v43, -v64
	v_add_f32_e64 v56, v36, v56
	v_add_f32_e64 v57, v37, v57
	v_exp_f32_e32 v42, v42
	v_add_f32_e64 v36, v38, v56
	v_add_f32_e64 v37, v39, v57
	v_exp_f32_e32 v43, v43
	v_cvt_pk_bf16_f32 v35, v38, v39
	v_add_f32_e64 v38, v40, v36
	v_add_f32_e64 v39, v41, v37
	v_cvt_pk_bf16_f32 v36, v40, v41
	v_add_f32_e64 v40, v44, -v64
	v_add_f32_e64 v41, v45, -v64
	v_add_f32_e64 v44, v46, -v64
	v_add_f32_e64 v45, v47, -v64
	v_exp_f32_e32 v40, v40
	v_exp_f32_e32 v41, v41
	v_exp_f32_e32 v44, v44
	v_exp_f32_e32 v45, v45
	v_add_f32_e64 v38, v42, v38
	v_add_f32_e64 v39, v43, v39
	v_cvt_pk_bf16_f32 v37, v42, v43
	s_nop 0
	v_add_f32_e64 v42, v40, v38
	v_add_f32_e64 v43, v41, v39
	v_cvt_pk_bf16_f32 v38, v40, v41
	v_cvt_pk_bf16_f32 v39, v44, v45
	s_nop 0
	v_add_f32_e64 v40, v44, v42
	v_add_f32_e64 v41, v45, v43
	v_add_f32_e64 v16, v16, -v64
	v_add_f32_e64 v17, v17, -v64
	v_add_f32_e64 v18, v18, -v64
	v_add_f32_e64 v19, v19, -v64
	v_exp_f32_e32 v16, v16
	v_exp_f32_e32 v17, v17
	v_exp_f32_e32 v18, v18
	v_exp_f32_e32 v19, v19
	v_add_f32_e64 v20, v20, -v64
	v_add_f32_e64 v21, v21, -v64
	v_add_f32_e64 v42, v16, v40
	v_add_f32_e64 v43, v17, v41
	v_exp_f32_e32 v20, v20
	v_exp_f32_e32 v21, v21
	v_add_f32_e64 v22, v22, -v64
	v_add_f32_e64 v23, v23, -v64
	v_cvt_pk_bf16_f32 v40, v16, v17
	v_add_f32_e64 v16, v18, v42
	v_add_f32_e64 v17, v19, v43
	v_exp_f32_e32 v22, v22
	v_exp_f32_e32 v23, v23
	v_cvt_pk_bf16_f32 v41, v18, v19
	v_add_f32_e64 v18, v24, -v64
	v_add_f32_e64 v19, v25, -v64
	v_add_f32_e64 v16, v20, v16
	v_add_f32_e64 v17, v21, v17
	v_exp_f32_e32 v18, v18
	v_exp_f32_e32 v19, v19
	v_cvt_pk_bf16_f32 v42, v20, v21
	v_add_f32_e64 v16, v22, v16
	v_add_f32_e64 v17, v23, v17
	v_add_f32_e64 v20, v26, -v64
	v_add_f32_e64 v21, v27, -v64
	v_cvt_pk_bf16_f32 v43, v22, v23
	v_add_f32_e64 v16, v18, v16
	v_add_f32_e64 v17, v19, v17
	v_exp_f32_e32 v20, v20
	v_exp_f32_e32 v21, v21
	v_cvt_pk_bf16_f32 v44, v18, v19
	v_add_f32_e64 v18, v28, -v64
	v_add_f32_e64 v19, v29, -v64
	v_add_f32_e64 v22, v30, -v64
	v_add_f32_e64 v23, v31, -v64
	v_exp_f32_e32 v18, v18
	v_exp_f32_e32 v19, v19
	v_exp_f32_e32 v22, v22
	v_exp_f32_e32 v23, v23
	v_add_f32_e64 v16, v20, v16
	v_add_f32_e64 v17, v21, v17
	v_cvt_pk_bf16_f32 v45, v20, v21
	v_cvt_pk_bf16_f32 v46, v18, v19
	v_cvt_pk_bf16_f32 v47, v22, v23
	s_nop 0
	v_add_f32_e64 v16, v18, v16
	v_add_f32_e64 v17, v19, v17
	s_nop 0
	v_add_f32_e64 v16, v22, v16
	v_add_f32_e64 v17, v23, v17
	v_add_f32_e64 v0, v0, -v64
	v_add_f32_e64 v1, v1, -v64
	v_add_f32_e64 v2, v2, -v64
	v_add_f32_e64 v3, v3, -v64
	v_exp_f32_e32 v0, v0
	v_exp_f32_e32 v1, v1
	v_exp_f32_e32 v2, v2
	v_exp_f32_e32 v3, v3
	v_add_f32_e64 v4, v4, -v64
	v_add_f32_e64 v5, v5, -v64
	v_add_f32_e64 v16, v0, v16
	v_add_f32_e64 v17, v1, v17
	v_exp_f32_e32 v4, v4
	v_exp_f32_e32 v5, v5
	v_add_f32_e64 v6, v6, -v64
	v_add_f32_e64 v7, v7, -v64
	v_cvt_pk_bf16_f32 v56, v0, v1
	v_add_f32_e64 v0, v2, v16
	v_add_f32_e64 v1, v3, v17
	v_exp_f32_e32 v6, v6
	v_exp_f32_e32 v7, v7
	v_cvt_pk_bf16_f32 v57, v2, v3
	v_add_f32_e64 v2, v8, -v64
	v_add_f32_e64 v3, v9, -v64
	v_add_f32_e64 v0, v4, v0
	v_add_f32_e64 v1, v5, v1
	v_exp_f32_e32 v2, v2
	v_exp_f32_e32 v3, v3
	v_cvt_pk_bf16_f32 v58, v4, v5
	v_add_f32_e64 v0, v6, v0
	v_add_f32_e64 v1, v7, v1
	v_add_f32_e64 v4, v10, -v64
	v_add_f32_e64 v5, v11, -v64
	v_cvt_pk_bf16_f32 v59, v6, v7
	v_add_f32_e64 v0, v2, v0
	v_add_f32_e64 v1, v3, v1
	v_exp_f32_e32 v4, v4
	v_exp_f32_e32 v5, v5
	v_cvt_pk_bf16_f32 v60, v2, v3
	v_add_f32_e64 v2, v12, -v64
	v_add_f32_e64 v3, v13, -v64
	v_add_f32_e64 v6, v14, -v64
	v_add_f32_e64 v7, v15, -v64
	v_exp_f32_e32 v2, v2
	v_exp_f32_e32 v3, v3
	v_exp_f32_e32 v6, v6
	v_exp_f32_e32 v7, v7
	v_add_f32_e64 v0, v4, v0
	v_add_f32_e64 v1, v5, v1
	v_cvt_pk_bf16_f32 v61, v4, v5
	v_cvt_pk_bf16_f32 v62, v2, v3
	v_cvt_pk_bf16_f32 v63, v6, v7
	s_nop 0
	v_add_f32_e64 v0, v2, v0
	v_add_f32_e64 v1, v3, v1
	s_nop 0
	v_add_f32_e64 v0, v6, v0
	v_add_f32_e64 v1, v7, v1
	v_add_f32_e64 v2, v202, -v64
	v_add_f32_e64 v3, v203, -v64
	v_add_f32_e64 v4, v200, -v64
	v_add_f32_e64 v5, v201, -v64
	v_exp_f32_e32 v2, v2
	v_exp_f32_e32 v3, v3
	v_exp_f32_e32 v4, v4
	v_exp_f32_e32 v5, v5
	v_cvt_pk_bf16_f32 v74, v2, v3
	v_add_f32_e64 v0, v2, v0
	v_add_f32_e64 v1, v3, v1
	v_add_f32_e64 v2, v198, -v64
	v_add_f32_e64 v3, v199, -v64
	v_add_f32_e64 v0, v4, v0
	v_add_f32_e64 v1, v5, v1
	v_exp_f32_e32 v2, v2
	v_exp_f32_e32 v3, v3
	v_add_f32_e64 v6, v90, -v64
	v_add_f32_e64 v7, v91, -v64
	v_cvt_pk_bf16_f32 v75, v4, v5
	v_cvt_pk_bf16_f32 v76, v2, v3
	v_add_f32_e64 v0, v2, v0
	v_add_f32_e64 v1, v3, v1
	v_exp_f32_e32 v6, v6
	v_exp_f32_e32 v7, v7
	v_add_f32_e64 v2, v72, -v64
	v_add_f32_e64 v3, v73, -v64
	v_add_f32_e64 v4, v70, -v64
	v_add_f32_e64 v5, v71, -v64
	v_exp_f32_e32 v2, v2
	v_exp_f32_e32 v3, v3
	v_add_f32_e64 v0, v6, v0
	v_add_f32_e64 v1, v7, v1
	v_exp_f32_e32 v4, v4
	v_exp_f32_e32 v5, v5
	v_cvt_pk_bf16_f32 v77, v6, v7
	v_add_f32_e64 v0, v2, v0
	v_add_f32_e64 v1, v3, v1
	v_cvt_pk_bf16_f32 v70, v2, v3
	v_add_f32_e64 v2, v68, -v64
	v_add_f32_e64 v3, v69, -v64
	v_add_f32_e64 v6, v66, -v64
	v_add_f32_e64 v7, v67, -v64
	v_exp_f32_e32 v2, v2
	v_exp_f32_e32 v3, v3
	v_exp_f32_e32 v6, v6
	v_exp_f32_e32 v7, v7
	v_add_f32_e64 v0, v4, v0
	v_add_f32_e64 v1, v5, v1
	v_cvt_pk_bf16_f32 v71, v4, v5
	v_cvt_pk_bf16_f32 v72, v2, v3
	v_cvt_pk_bf16_f32 v73, v6, v7
	s_nop 0
	v_add_f32_e64 v0, v2, v0
	v_add_f32_e64 v1, v3, v1
	s_nop 0
	v_add_f32_e64 v78, v6, v0
	v_add_f32_e64 v79, v7, v1
	ds_read_b64_tr_b16 v[0:1], v208 offset:55296
	ds_read_b64_tr_b16 v[2:3], v208 offset:56448
	ds_read_b64_tr_b16 v[18:19], v208 offset:56512
	ds_read_b64_tr_b16 v[16:17], v208 offset:55360
	s_waitcnt lgkmcnt(2)
	v_mfma_f32_32x32x16_bf16 v[0:15], v[48:51], v[0:3], 0
	s_waitcnt lgkmcnt(0)
	v_mfma_f32_32x32x16_bf16 v[16:31], v[48:51], v[16:19], 0
	ds_read_b64_tr_b16 v[48:49], v208 offset:57600
	ds_read_b64_tr_b16 v[50:51], v208 offset:58752
	ds_read_b64_tr_b16 v[68:69], v208 offset:58816
	ds_read_b64_tr_b16 v[66:67], v208 offset:57664
	s_waitcnt lgkmcnt(2)
	v_mfma_f32_32x32x16_bf16 v[0:15], v[52:55], v[48:51], v[0:15]
	s_waitcnt lgkmcnt(0)
	v_mfma_f32_32x32x16_bf16 v[16:31], v[52:55], v[66:69], v[16:31]
	ds_read_b64_tr_b16 v[48:49], v208 offset:59904
	ds_read_b64_tr_b16 v[50:51], v208 offset:61056
	ds_read_b64_tr_b16 v[54:55], v208 offset:61120
	ds_read_b64_tr_b16 v[52:53], v208 offset:59968
	s_waitcnt lgkmcnt(2)
	v_mfma_f32_32x32x16_bf16 v[0:15], v[32:35], v[48:51], v[0:15]
	s_waitcnt lgkmcnt(0)
	v_mfma_f32_32x32x16_bf16 v[16:31], v[32:35], v[52:55], v[16:31]
	ds_read_b64_tr_b16 v[32:33], v208 offset:62208
	ds_read_b64_tr_b16 v[34:35], v208 offset:63360
	ds_read_b64_tr_b16 v[50:51], v208 offset:63424
	ds_read_b64_tr_b16 v[48:49], v208 offset:62272
	s_waitcnt lgkmcnt(2)
	v_mfma_f32_32x32x16_bf16 v[0:15], v[36:39], v[32:35], v[0:15]
	s_waitcnt lgkmcnt(0)
	v_mfma_f32_32x32x16_bf16 v[16:31], v[36:39], v[48:51], v[16:31]
	ds_read_b64_tr_b16 v[32:33], v208 offset:64512
	ds_read_b64_tr_b16 v[34:35], v209 offset:10368
	ds_read_b64_tr_b16 v[38:39], v209 offset:10432
	ds_read_b64_tr_b16 v[36:37], v208 offset:64576
	s_waitcnt lgkmcnt(2)
	v_mfma_f32_32x32x16_bf16 v[0:15], v[40:43], v[32:35], v[0:15]
	s_waitcnt lgkmcnt(0)
	v_mfma_f32_32x32x16_bf16 v[16:31], v[40:43], v[36:39], v[16:31]
	ds_read_b64_tr_b16 v[32:33], v209 offset:11520
	ds_read_b64_tr_b16 v[34:35], v209 offset:12672
	ds_read_b64_tr_b16 v[38:39], v209 offset:12736
	ds_read_b64_tr_b16 v[36:37], v209 offset:11584
	s_waitcnt lgkmcnt(2)
	v_mfma_f32_32x32x16_bf16 v[0:15], v[44:47], v[32:35], v[0:15]
	s_waitcnt lgkmcnt(0)
	v_mfma_f32_32x32x16_bf16 v[16:31], v[44:47], v[36:39], v[16:31]
	ds_read_b64_tr_b16 v[32:33], v209 offset:13824
	ds_read_b64_tr_b16 v[34:35], v209 offset:14976
	ds_read_b64_tr_b16 v[38:39], v209 offset:15040
	ds_read_b64_tr_b16 v[36:37], v209 offset:13888
	s_waitcnt lgkmcnt(2)
	v_mfma_f32_32x32x16_bf16 v[0:15], v[56:59], v[32:35], v[0:15]
	s_waitcnt lgkmcnt(0)
	v_mfma_f32_32x32x16_bf16 v[16:31], v[56:59], v[36:39], v[16:31]
	ds_read_b64_tr_b16 v[32:33], v209 offset:16128
	ds_read_b64_tr_b16 v[34:35], v209 offset:17280
	ds_read_b64_tr_b16 v[38:39], v209 offset:17344
	ds_read_b64_tr_b16 v[36:37], v209 offset:16192
	s_waitcnt lgkmcnt(2)
	v_mfma_f32_32x32x16_bf16 v[0:15], v[60:63], v[32:35], v[0:15]
	s_waitcnt lgkmcnt(0)
	v_mfma_f32_32x32x16_bf16 v[16:31], v[60:63], v[36:39], v[16:31]
	ds_read_b64_tr_b16 v[32:33], v209 offset:18432
	ds_read_b64_tr_b16 v[34:35], v209 offset:19584
	ds_read_b64_tr_b16 v[38:39], v209 offset:19648
	ds_read_b64_tr_b16 v[36:37], v209 offset:18496
	s_waitcnt lgkmcnt(2)
	v_mfma_f32_32x32x16_bf16 v[0:15], v[74:77], v[32:35], v[0:15]
	s_waitcnt lgkmcnt(0)
	v_mfma_f32_32x32x16_bf16 v[16:31], v[74:77], v[36:39], v[16:31]
	ds_read_b64_tr_b16 v[32:33], v209 offset:20736
	ds_read_b64_tr_b16 v[34:35], v209 offset:21888
	ds_read_b64_tr_b16 v[38:39], v209 offset:21952
	ds_read_b64_tr_b16 v[36:37], v209 offset:20800
	s_waitcnt lgkmcnt(2)
	v_mfma_f32_32x32x16_bf16 v[0:15], v[70:73], v[32:35], v[0:15]
	v_add_f32_e32 v32, v78, v79
	ds_bpermute_b32 v33, v65, v32
	s_waitcnt lgkmcnt(1)
	v_mfma_f32_32x32x16_bf16 v[16:31], v[70:73], v[36:39], v[16:31]
	s_and_saveexec_b64 s[0:1], s[4:5]
	s_cbranch_execz .LBB0_522
	s_waitcnt lgkmcnt(0)
	v_add_f32_e32 v32, v32, v33
	v_log_f32_e32 v33, v32
	s_nop 0
	v_add_f32_e32 v33, v64, v33
	s_waitcnt vmcnt(8)
	v_max3_f32 v34, v33, v227, v89
	v_sub_f32_e32 v33, v33, v34
	v_sub_f32_e32 v35, v227, v34
	v_sub_f32_e32 v34, v89, v34
	v_exp_f32_e32 v33, v33
	v_exp_f32_e32 v35, v35
	v_exp_f32_e32 v34, v34
	v_add_f32_e32 v36, v33, v35
	v_add_f32_e32 v36, v34, v36
	v_div_scale_f32 v37, s[18:19], v36, v36, 1.0
	v_rcp_f32_e32 v38, v37
	v_div_scale_f32 v39, vcc, 1.0, v36, 1.0
	v_fma_f32 v40, -v37, v38, 1.0
	v_fmac_f32_e32 v38, v40, v38
	v_mul_f32_e32 v40, v39, v38
	v_fma_f32 v41, -v37, v40, v39
	v_fmac_f32_e32 v40, v41, v38
	v_fma_f32 v37, -v37, v40, v39
	v_div_fmas_f32 v37, v37, v38, v40
	v_div_fixup_f32 v36, v37, v36, 1.0
	v_mul_f32_e32 v33, v33, v36
	v_div_scale_f32 v37, s[18:19], v32, v32, v33
	v_rcp_f32_e32 v38, v37
	v_div_scale_f32 v39, vcc, v33, v32, v33
	v_fma_f32 v40, -v37, v38, 1.0
	v_fmac_f32_e32 v38, v40, v38
	v_mul_f32_e32 v40, v39, v38
	v_fma_f32 v41, -v37, v40, v39
	v_fmac_f32_e32 v40, v41, v38
	v_fma_f32 v37, -v37, v40, v39
	v_div_fmas_f32 v37, v37, v38, v40
	v_div_fixup_f32 v32, v37, v32, v33
	v_mul_f32_e32 v33, v35, v36
	v_add_u32_e32 v35, 0x1000, v223
	ds_write2_b32 v35, v32, v33 offset0:128 offset1:160
	v_mul_f32_e32 v32, v34, v36
	ds_write_b32 v223, v32 offset:4864
	s_branch .LBB0_522

.LBB0_1240:
	s_waitcnt lgkmcnt(0)
	s_barrier
	v_mov_b32_e32 v5, s98
	v_cndmask_b32_e64 v0, 0, v190, s[12:13]
	v_fmac_f32_e32 v0, -0.5, v4
	v_exp_f32_e32 v0, v0
	s_add_i32 s12, s88, s63
	v_mul_f32_e32 v97, 0x3fb8aa3b, v5
	v_ldexp_f32 v0, v0, s17
	v_mul_f32_e32 v72, 0x3fb8aa3b, v0
	v_add_u32_e32 v0, v167, v168
	v_mov_b32_e32 v214, v169
	ds_read_b128 v[192:195], v0
	ds_read_b128 v[154:157], v0 offset:32
	ds_read_b128 v[150:153], v0 offset:64
	ds_read_b128 v[146:149], v0 offset:96
	s_cmpk_gt_i32 s12, 0x7f
	v_cvt_f32_i32_e32 v0, v214
	v_mul_f32_e32 v9, 0, v72
	s_cselect_b64 vcc, -1, 0
	v_cndmask_b32_e32 v10, v191, v9, vcc
	v_mul_f32_e64 v8, -v72, v0
	v_fma_f32 v205, -v72, v0, v72
	ds_read_b128 v[0:3], v179
	ds_read_b128 v[4:7], v179 offset:32
	v_fma_f32 v204, 0, v72, v8
	v_fma_f32 v206, v72, s18, v8
	v_fma_f32 v207, v72, s19, v8
	v_fma_f32 v208, v72, s30, v8
	v_fma_f32 v209, v72, s31, v8
	v_fma_f32 v210, v72, s36, v8
	v_fma_f32 v211, v72, s37, v8
	v_fma_f32 v212, v72, s44, v8
	v_fma_f32 v213, v72, s45, v8
	v_fma_f32 v74, v72, s46, v8
	v_fma_f32 v75, v72, s47, v8
	v_fma_f32 v76, v72, s48, v8
	v_fma_f32 v77, v72, s49, v8
	v_fma_f32 v78, v72, s52, v8
	v_fma_f32 v79, v72, s53, v8
	v_add_f32_e64 v62, v10, v78
	v_add_f32_e64 v63, v10, v79
	v_add_f32_e64 v60, v10, v76
	v_add_f32_e64 v61, v10, v77
	v_add_f32_e64 v58, v10, v74
	v_add_f32_e64 v59, v10, v75
	v_add_f32_e64 v56, v10, v212
	v_add_f32_e64 v57, v10, v213
	v_add_f32_e64 v54, v10, v210
	v_add_f32_e64 v55, v10, v211
	v_add_f32_e64 v52, v10, v208
	v_add_f32_e64 v53, v10, v209
	v_add_f32_e64 v50, v10, v206
	v_add_f32_e64 v51, v10, v207
	v_add_f32_e64 v48, v10, v204
	v_add_f32_e64 v49, v10, v205
	s_cmpk_gt_i32 s12, 0x5f
	v_mul_f32_e32 v12, 0x42000000, v72
	s_waitcnt lgkmcnt(1)
	v_mfma_f32_32x32x16_bf16 v[48:63], v[0:3], v[192:195], v[48:63]
	s_cselect_b64 vcc, -1, 0
	v_cndmask_b32_e32 v12, v191, v12, vcc
	v_add_f32_e64 v46, v12, v78
	v_add_f32_e64 v47, v12, v79
	v_add_f32_e64 v44, v12, v76
	v_add_f32_e64 v45, v12, v77
	v_add_f32_e64 v42, v12, v74
	v_add_f32_e64 v43, v12, v75
	v_add_f32_e64 v40, v12, v212
	v_add_f32_e64 v41, v12, v213
	v_add_f32_e64 v38, v12, v210
	v_add_f32_e64 v39, v12, v211
	s_waitcnt lgkmcnt(0)
	v_mfma_f32_32x32x16_bf16 v[48:63], v[4:7], v[154:157], v[48:63]
	ds_read_b128 v[0:3], v179 offset:64
	ds_read_b128 v[4:7], v179 offset:96
	v_add_f32_e64 v36, v12, v208
	v_add_f32_e64 v37, v12, v209
	v_add_f32_e64 v34, v12, v206
	v_add_f32_e64 v35, v12, v207
	v_add_f32_e64 v32, v12, v204
	v_add_f32_e64 v33, v12, v205
	s_cmp_gt_i32 s12, 63
	v_mul_f32_e32 v12, 0x42800000, v72
	s_cselect_b64 vcc, -1, 0
	s_waitcnt lgkmcnt(1)
	v_mfma_f32_32x32x16_bf16 v[48:63], v[0:3], v[150:153], v[48:63]
	ds_read_b128 v[0:3], v181
	ds_read_b128 v[8:11], v181 offset:32
	v_cndmask_b32_e32 v12, v191, v12, vcc
	v_add_f32_e64 v30, v12, v78
	v_add_f32_e64 v31, v12, v79
	v_add_f32_e64 v28, v12, v76
	v_add_f32_e64 v29, v12, v77
	v_add_f32_e64 v26, v12, v74
	v_add_f32_e64 v27, v12, v75
	v_add_f32_e64 v24, v12, v212
	v_add_f32_e64 v25, v12, v213
	v_add_f32_e64 v22, v12, v210
	v_add_f32_e64 v23, v12, v211
	s_waitcnt lgkmcnt(1)
	v_mfma_f32_32x32x16_bf16 v[32:47], v[0:3], v[192:195], v[32:47]
	v_add_f32_e64 v20, v12, v208
	v_add_f32_e64 v21, v12, v209
	v_add_f32_e64 v18, v12, v206
	v_add_f32_e64 v19, v12, v207
	v_add_f32_e64 v16, v12, v204
	v_add_f32_e64 v17, v12, v205
	s_cmp_gt_i32 s12, 31
	s_cselect_b64 vcc, -1, 0
	s_cmp_gt_i32 s12, -1
	s_waitcnt lgkmcnt(0)
	v_mfma_f32_32x32x16_bf16 v[32:47], v[8:11], v[154:157], v[32:47]
	v_mfma_f32_32x32x16_bf16 v[48:63], v[4:7], v[146:149], v[48:63]
	ds_read_b128 v[0:3], v181 offset:64
	ds_read_b128 v[4:7], v181 offset:96
	s_waitcnt lgkmcnt(1)
	v_mfma_f32_32x32x16_bf16 v[32:47], v[0:3], v[150:153], v[32:47]
	ds_read_b128 v[0:3], v184
	ds_read_b128 v[8:11], v184 offset:32
	s_waitcnt lgkmcnt(1)
	v_mfma_f32_32x32x16_bf16 v[16:31], v[0:3], v[192:195], v[16:31]
	s_waitcnt lgkmcnt(0)
	v_mfma_f32_32x32x16_bf16 v[16:31], v[8:11], v[154:157], v[16:31]
	v_mfma_f32_32x32x16_bf16 v[32:47], v[4:7], v[146:149], v[32:47]
	ds_read_b128 v[0:3], v184 offset:64
	ds_read_b128 v[4:7], v184 offset:96
	ds_read_b128 v[64:67], v185
	ds_read_b128 v[68:71], v185 offset:32
	s_waitcnt lgkmcnt(3)
	v_mfma_f32_32x32x16_bf16 v[16:31], v[0:3], v[150:153], v[16:31]
	v_mul_f32_e32 v0, 0x42c00000, v72
	v_cndmask_b32_e32 v0, v191, v0, vcc
	v_add_f32_e64 v14, v0, v78
	v_add_f32_e64 v15, v0, v79
	v_add_f32_e64 v12, v0, v76
	v_add_f32_e64 v13, v0, v77
	v_add_f32_e64 v10, v0, v74
	v_add_f32_e64 v11, v0, v75
	v_add_f32_e64 v8, v0, v212
	v_add_f32_e64 v9, v0, v213
	v_add_f32_e64 v2, v0, v206
	v_add_f32_e64 v3, v0, v207
	s_waitcnt lgkmcnt(2)
	v_mfma_f32_32x32x16_bf16 v[16:31], v[4:7], v[146:149], v[16:31]
	v_add_f32_e64 v6, v0, v210
	v_add_f32_e64 v7, v0, v211
	v_add_f32_e64 v4, v0, v208
	v_add_f32_e64 v5, v0, v209
	v_add_f32_e64 v1, v0, v205
	v_add_f32_e64 v0, v0, v204
	s_cselect_b64 vcc, -1, 0
	s_waitcnt lgkmcnt(1)
	v_mfma_f32_32x32x16_bf16 v[0:15], v[64:67], v[192:195], v[0:15]
	s_waitcnt lgkmcnt(0)
	v_mfma_f32_32x32x16_bf16 v[0:15], v[68:71], v[154:157], v[0:15]
	ds_read_b128 v[64:67], v185 offset:64
	ds_read_b128 v[68:71], v185 offset:96
	ds_read_b128 v[196:199], v186
	ds_read_b128 v[200:203], v186 offset:32
	s_waitcnt lgkmcnt(3)
	v_mfma_f32_32x32x16_bf16 v[0:15], v[64:67], v[150:153], v[0:15]
	v_mul_f32_e32 v64, 0x43000000, v72
	v_cndmask_b32_e32 v64, v191, v64, vcc
	v_add_f32_e64 v78, v64, v78
	v_add_f32_e64 v79, v64, v79
	v_add_f32_e64 v76, v64, v76
	v_add_f32_e64 v77, v64, v77
	v_add_f32_e64 v74, v64, v74
	v_add_f32_e64 v75, v64, v75
	v_add_f32_e64 v72, v64, v212
	v_add_f32_e64 v73, v64, v213
	v_add_f32_e64 v66, v64, v206
	v_add_f32_e64 v67, v64, v207
	s_waitcnt lgkmcnt(2)
	v_mfma_f32_32x32x16_bf16 v[0:15], v[68:71], v[146:149], v[0:15]
	v_add_f32_e64 v70, v64, v210
	v_add_f32_e64 v71, v64, v211
	v_add_f32_e64 v68, v64, v208
	v_add_f32_e64 v69, v64, v209
	v_add_f32_e64 v65, v64, v205
	v_add_f32_e64 v64, v64, v204
	s_waitcnt lgkmcnt(1)
	s_nop 0
	v_mfma_f32_32x32x16_bf16 v[64:79], v[196:199], v[192:195], v[64:79]
	s_waitcnt lgkmcnt(0)
	v_mfma_f32_32x32x16_bf16 v[64:79], v[200:203], v[154:157], v[64:79]
	ds_read_b128 v[154:157], v186 offset:64
	ds_read_b128 v[192:195], v186 offset:96
	s_waitcnt lgkmcnt(1)
	v_mfma_f32_32x32x16_bf16 v[64:79], v[154:157], v[150:153], v[64:79]
	s_waitcnt lgkmcnt(0)
	v_mfma_f32_32x32x16_bf16 v[64:79], v[192:195], v[146:149], v[64:79]
	v_cmp_gt_i32_e32 vcc, s65, v214
	s_nop 1
	v_cndmask_b32_e32 v48, v191, v48, vcc
	s_nop 7
	v_cndmask_b32_e32 v152, v64, v191, vcc
	v_cmp_gt_i32_e32 vcc, s68, v214
	s_nop 1
	v_cndmask_b32_e32 v49, v191, v49, vcc
	v_cndmask_b32_e32 v153, v65, v191, vcc
	v_cmp_gt_i32_e32 vcc, s69, v214
	v_max3_f32 v64, v48, s67, v49
	s_nop 0
	v_cndmask_b32_e32 v50, v191, v50, vcc
	v_cndmask_b32_e32 v150, v66, v191, vcc
	v_cmp_gt_i32_e32 vcc, s70, v214
	s_nop 1
	v_cndmask_b32_e32 v51, v191, v51, vcc
	v_cndmask_b32_e32 v151, v67, v191, vcc
	v_cmp_gt_i32_e32 vcc, s71, v214
	v_max3_f32 v64, v64, v50, v51
	s_nop 0
	v_cndmask_b32_e32 v52, v191, v52, vcc
	v_cndmask_b32_e32 v148, v68, v191, vcc
	v_cmp_gt_i32_e32 vcc, s72, v214
	s_nop 1
	v_cndmask_b32_e32 v53, v191, v53, vcc
	v_cndmask_b32_e32 v149, v69, v191, vcc
	v_cmp_gt_i32_e32 vcc, s73, v214
	v_max3_f32 v64, v64, v52, v53
	s_nop 0
	v_cndmask_b32_e32 v54, v191, v54, vcc
	v_cndmask_b32_e32 v146, v70, v191, vcc
	v_cmp_gt_i32_e32 vcc, s74, v214
	s_nop 1
	v_cndmask_b32_e32 v55, v191, v55, vcc
	v_cndmask_b32_e32 v147, v71, v191, vcc
	v_cmp_gt_i32_e32 vcc, s64, v214
	v_max3_f32 v64, v64, v54, v55
	s_nop 0
	v_cndmask_b32_e32 v56, v191, v56, vcc
	v_cndmask_b32_e32 v72, v72, v191, vcc
	v_cmp_gt_i32_e32 vcc, s75, v214
	s_nop 1
	v_cndmask_b32_e32 v57, v191, v57, vcc
	v_cndmask_b32_e32 v73, v73, v191, vcc
	v_cmp_gt_i32_e32 vcc, s76, v214
	v_max3_f32 v64, v64, v56, v57
	s_nop 0
	v_cndmask_b32_e32 v58, v191, v58, vcc
	v_cndmask_b32_e32 v70, v74, v191, vcc
	v_cmp_gt_i32_e32 vcc, s77, v214
	s_nop 1
	v_cndmask_b32_e32 v59, v191, v59, vcc
	v_cndmask_b32_e32 v71, v75, v191, vcc
	v_cmp_gt_i32_e32 vcc, s82, v214
	v_max3_f32 v64, v64, v58, v59
	s_nop 0
	v_cndmask_b32_e32 v60, v191, v60, vcc
	v_cndmask_b32_e32 v68, v76, v191, vcc
	v_cmp_gt_i32_e32 vcc, s83, v214
	s_nop 1
	v_cndmask_b32_e32 v61, v191, v61, vcc
	v_cndmask_b32_e32 v69, v77, v191, vcc
	v_cmp_gt_i32_e32 vcc, s84, v214
	v_max3_f32 v64, v64, v60, v61
	s_nop 0
	v_cndmask_b32_e32 v62, v191, v62, vcc
	v_cndmask_b32_e32 v66, v78, v191, vcc
	v_cmp_gt_i32_e32 vcc, s85, v214
	s_nop 1
	v_cndmask_b32_e32 v63, v191, v63, vcc
	v_max3_f32 v64, v64, v62, v63
	v_max3_f32 v64, v64, v32, v33
	v_max3_f32 v64, v64, v34, v35
	v_max3_f32 v64, v64, v36, v37
	v_max3_f32 v64, v64, v38, v39
	v_max3_f32 v64, v64, v40, v41
	v_max3_f32 v64, v64, v42, v43
	v_max3_f32 v64, v64, v44, v45
	v_max3_f32 v64, v64, v46, v47
	v_max3_f32 v64, v64, v16, v17
	v_max3_f32 v64, v64, v18, v19
	v_max3_f32 v64, v64, v20, v21
	v_max3_f32 v64, v64, v22, v23
	v_max3_f32 v64, v64, v24, v25
	v_max3_f32 v64, v64, v26, v27
	v_max3_f32 v64, v64, v28, v29
	v_max3_f32 v64, v64, v30, v31
	v_max3_f32 v64, v64, v0, v1
	v_max3_f32 v64, v64, v2, v3
	v_max3_f32 v64, v64, v4, v5
	v_max3_f32 v64, v64, v6, v7
	v_max3_f32 v64, v64, v8, v9
	v_max3_f32 v64, v64, v10, v11
	v_max3_f32 v64, v64, v12, v13
	v_max3_f32 v64, v64, v14, v15
	v_max3_f32 v64, v64, v152, v153
	v_max3_f32 v64, v64, v150, v151
	v_max3_f32 v64, v64, v148, v149
	v_max3_f32 v64, v64, v146, v147
	v_max3_f32 v64, v64, v72, v73
	v_max3_f32 v64, v64, v70, v71
	v_cndmask_b32_e32 v67, v79, v191, vcc
	v_max3_f32 v64, v64, v68, v69
	v_max3_f32 v64, v64, v66, v67
	v_and_b32_e32 v74, 64, v187
	v_xor_b32_e32 v65, 32, v187
	v_add_u32_e32 v74, 64, v74
	v_cmp_lt_i32_e32 vcc, v65, v74
	s_nop 1
	v_cndmask_b32_e32 v65, v187, v65, vcc
	v_lshlrev_b32_e32 v65, 2, v65
	ds_bpermute_b32 v74, v65, v64
	s_waitcnt lgkmcnt(0)
	v_max3_f32 v64, v64, v74, v97
	v_add_f32_e64 v48, v48, -v64
	v_add_f32_e64 v49, v49, -v64
	v_add_f32_e64 v50, v50, -v64
	v_add_f32_e64 v51, v51, -v64
	v_exp_f32_e32 v48, v48
	v_exp_f32_e32 v49, v49
	v_exp_f32_e32 v50, v50
	v_exp_f32_e32 v51, v51
	v_add_f32_e64 v52, v52, -v64
	v_add_f32_e64 v53, v53, -v64
	v_add_f32_e64 v54, v54, -v64
	v_add_f32_e64 v55, v55, -v64
	v_exp_f32_e32 v52, v52
	v_exp_f32_e32 v53, v53
	v_exp_f32_e32 v54, v54
	v_exp_f32_e32 v55, v55
	v_add_f32_e64 v56, v56, -v64
	v_add_f32_e64 v57, v57, -v64
	v_add_f32_e64 v74, v48, 0
	v_add_f32_e64 v75, v49, 0
	v_exp_f32_e32 v56, v56
	v_exp_f32_e32 v57, v57
	v_add_f32_e64 v74, v50, v74
	v_add_f32_e64 v75, v51, v75
	v_cvt_pk_bf16_f32 v48, v48, v49
	v_cvt_pk_bf16_f32 v49, v50, v51
	v_cvt_pk_bf16_f32 v50, v52, v53
	v_add_f32_e64 v58, v58, -v64
	v_add_f32_e64 v59, v59, -v64
	v_add_f32_e64 v74, v52, v74
	v_add_f32_e64 v75, v53, v75
	v_exp_f32_e32 v58, v58
	v_add_f32_e64 v52, v54, v74
	v_add_f32_e64 v53, v55, v75
	v_exp_f32_e32 v59, v59
	v_cvt_pk_bf16_f32 v51, v54, v55
	v_add_f32_e64 v54, v56, v52
	v_add_f32_e64 v55, v57, v53
	v_cvt_pk_bf16_f32 v52, v56, v57
	v_add_f32_e64 v56, v60, -v64
	v_add_f32_e64 v57, v61, -v64
	v_add_f32_e64 v60, v62, -v64
	v_add_f32_e64 v61, v63, -v64
	v_exp_f32_e32 v56, v56
	v_exp_f32_e32 v57, v57
	v_exp_f32_e32 v60, v60
	v_exp_f32_e32 v61, v61
	v_add_f32_e64 v54, v58, v54
	v_add_f32_e64 v55, v59, v55
	v_cvt_pk_bf16_f32 v53, v58, v59
	s_nop 0
	v_add_f32_e64 v58, v56, v54
	v_add_f32_e64 v59, v57, v55
	v_cvt_pk_bf16_f32 v54, v56, v57
	v_cvt_pk_bf16_f32 v55, v60, v61
	s_nop 0
	v_add_f32_e64 v56, v60, v58
	v_add_f32_e64 v57, v61, v59
	v_add_f32_e64 v32, v32, -v64
	v_add_f32_e64 v33, v33, -v64
	v_add_f32_e64 v34, v34, -v64
	v_add_f32_e64 v35, v35, -v64
	v_exp_f32_e32 v32, v32
	v_exp_f32_e32 v33, v33
	v_exp_f32_e32 v34, v34
	v_exp_f32_e32 v35, v35
	v_add_f32_e64 v36, v36, -v64
	v_add_f32_e64 v37, v37, -v64
	v_add_f32_e64 v38, v38, -v64
	v_add_f32_e64 v39, v39, -v64
	v_exp_f32_e32 v36, v36
	v_exp_f32_e32 v37, v37
	v_exp_f32_e32 v38, v38
	v_exp_f32_e32 v39, v39
	v_add_f32_e64 v40, v40, -v64
	v_add_f32_e64 v41, v41, -v64
	v_add_f32_e64 v56, v32, v56
	v_add_f32_e64 v57, v33, v57
	v_exp_f32_e32 v40, v40
	v_exp_f32_e32 v41, v41
	v_add_f32_e64 v56, v34, v56
	v_add_f32_e64 v57, v35, v57
	v_cvt_pk_bf16_f32 v32, v32, v33
	v_cvt_pk_bf16_f32 v33, v34, v35
	v_cvt_pk_bf16_f32 v34, v36, v37
	v_add_f32_e64 v42, v42, -v64
	v_add_f32_e64 v43, v43, -v64
	v_add_f32_e64 v56, v36, v56
	v_add_f32_e64 v57, v37, v57
	v_exp_f32_e32 v42, v42
	v_add_f32_e64 v36, v38, v56
	v_add_f32_e64 v37, v39, v57
	v_exp_f32_e32 v43, v43
	v_cvt_pk_bf16_f32 v35, v38, v39
	v_add_f32_e64 v38, v40, v36
	v_add_f32_e64 v39, v41, v37
	v_cvt_pk_bf16_f32 v36, v40, v41
	v_add_f32_e64 v40, v44, -v64
	v_add_f32_e64 v41, v45, -v64
	v_add_f32_e64 v44, v46, -v64
	v_add_f32_e64 v45, v47, -v64
	v_exp_f32_e32 v40, v40
	v_exp_f32_e32 v41, v41
	v_exp_f32_e32 v44, v44
	v_exp_f32_e32 v45, v45
	v_add_f32_e64 v38, v42, v38
	v_add_f32_e64 v39, v43, v39
	v_cvt_pk_bf16_f32 v37, v42, v43
	s_nop 0
	v_add_f32_e64 v42, v40, v38
	v_add_f32_e64 v43, v41, v39
	v_cvt_pk_bf16_f32 v38, v40, v41
	v_cvt_pk_bf16_f32 v39, v44, v45
	s_nop 0
	v_add_f32_e64 v40, v44, v42
	v_add_f32_e64 v41, v45, v43
	v_add_f32_e64 v16, v16, -v64
	v_add_f32_e64 v17, v17, -v64
	v_add_f32_e64 v18, v18, -v64
	v_add_f32_e64 v19, v19, -v64
	v_exp_f32_e32 v16, v16
	v_exp_f32_e32 v17, v17
	v_exp_f32_e32 v18, v18
	v_exp_f32_e32 v19, v19
	v_add_f32_e64 v20, v20, -v64
	v_add_f32_e64 v21, v21, -v64
	v_add_f32_e64 v42, v16, v40
	v_add_f32_e64 v43, v17, v41
	v_exp_f32_e32 v20, v20
	v_exp_f32_e32 v21, v21
	v_add_f32_e64 v22, v22, -v64
	v_add_f32_e64 v23, v23, -v64
	v_cvt_pk_bf16_f32 v40, v16, v17
	v_add_f32_e64 v16, v18, v42
	v_add_f32_e64 v17, v19, v43
	v_exp_f32_e32 v22, v22
	v_exp_f32_e32 v23, v23
	v_cvt_pk_bf16_f32 v41, v18, v19
	v_add_f32_e64 v18, v24, -v64
	v_add_f32_e64 v19, v25, -v64
	v_add_f32_e64 v16, v20, v16
	v_add_f32_e64 v17, v21, v17
	v_exp_f32_e32 v18, v18
	v_exp_f32_e32 v19, v19
	v_cvt_pk_bf16_f32 v42, v20, v21
	v_add_f32_e64 v16, v22, v16
	v_add_f32_e64 v17, v23, v17
	v_add_f32_e64 v20, v26, -v64
	v_add_f32_e64 v21, v27, -v64
	v_cvt_pk_bf16_f32 v43, v22, v23
	v_add_f32_e64 v16, v18, v16
	v_add_f32_e64 v17, v19, v17
	v_exp_f32_e32 v20, v20
	v_exp_f32_e32 v21, v21
	v_cvt_pk_bf16_f32 v44, v18, v19
	v_add_f32_e64 v18, v28, -v64
	v_add_f32_e64 v19, v29, -v64
	v_add_f32_e64 v22, v30, -v64
	v_add_f32_e64 v23, v31, -v64
	v_exp_f32_e32 v18, v18
	v_exp_f32_e32 v19, v19
	v_exp_f32_e32 v22, v22
	v_exp_f32_e32 v23, v23
	v_add_f32_e64 v16, v20, v16
	v_add_f32_e64 v17, v21, v17
	v_cvt_pk_bf16_f32 v45, v20, v21
	v_cvt_pk_bf16_f32 v46, v18, v19
	v_cvt_pk_bf16_f32 v47, v22, v23
	s_nop 0
	v_add_f32_e64 v16, v18, v16
	v_add_f32_e64 v17, v19, v17
	s_nop 0
	v_add_f32_e64 v16, v22, v16
	v_add_f32_e64 v17, v23, v17
	v_add_f32_e64 v0, v0, -v64
	v_add_f32_e64 v1, v1, -v64
	v_add_f32_e64 v2, v2, -v64
	v_add_f32_e64 v3, v3, -v64
	v_exp_f32_e32 v0, v0
	v_exp_f32_e32 v1, v1
	v_exp_f32_e32 v2, v2
	v_exp_f32_e32 v3, v3
	v_add_f32_e64 v4, v4, -v64
	v_add_f32_e64 v5, v5, -v64
	v_add_f32_e64 v16, v0, v16
	v_add_f32_e64 v17, v1, v17
	v_exp_f32_e32 v4, v4
	v_exp_f32_e32 v5, v5
	v_add_f32_e64 v6, v6, -v64
	v_add_f32_e64 v7, v7, -v64
	v_cvt_pk_bf16_f32 v56, v0, v1
	v_add_f32_e64 v0, v2, v16
	v_add_f32_e64 v1, v3, v17
	v_exp_f32_e32 v6, v6
	v_exp_f32_e32 v7, v7
	v_cvt_pk_bf16_f32 v57, v2, v3
	v_add_f32_e64 v2, v8, -v64
	v_add_f32_e64 v3, v9, -v64
	v_add_f32_e64 v0, v4, v0
	v_add_f32_e64 v1, v5, v1
	v_exp_f32_e32 v2, v2
	v_exp_f32_e32 v3, v3
	v_cvt_pk_bf16_f32 v58, v4, v5
	v_add_f32_e64 v0, v6, v0
	v_add_f32_e64 v1, v7, v1
	v_add_f32_e64 v4, v10, -v64
	v_add_f32_e64 v5, v11, -v64
	v_cvt_pk_bf16_f32 v59, v6, v7
	v_add_f32_e64 v0, v2, v0
	v_add_f32_e64 v1, v3, v1
	v_exp_f32_e32 v4, v4
	v_exp_f32_e32 v5, v5
	v_cvt_pk_bf16_f32 v60, v2, v3
	v_add_f32_e64 v2, v12, -v64
	v_add_f32_e64 v3, v13, -v64
	v_add_f32_e64 v6, v14, -v64
	v_add_f32_e64 v7, v15, -v64
	v_exp_f32_e32 v2, v2
	v_exp_f32_e32 v3, v3
	v_exp_f32_e32 v6, v6
	v_exp_f32_e32 v7, v7
	v_add_f32_e64 v0, v4, v0
	v_add_f32_e64 v1, v5, v1
	v_cvt_pk_bf16_f32 v61, v4, v5
	v_cvt_pk_bf16_f32 v62, v2, v3
	v_cvt_pk_bf16_f32 v63, v6, v7
	s_nop 0
	v_add_f32_e64 v0, v2, v0
	v_add_f32_e64 v1, v3, v1
	s_nop 0
	v_add_f32_e64 v0, v6, v0
	v_add_f32_e64 v1, v7, v1
	v_add_f32_e64 v2, v152, -v64
	v_add_f32_e64 v3, v153, -v64
	v_add_f32_e64 v4, v150, -v64
	v_add_f32_e64 v5, v151, -v64
	v_exp_f32_e32 v2, v2
	v_exp_f32_e32 v3, v3
	v_exp_f32_e32 v4, v4
	v_exp_f32_e32 v5, v5
	v_cvt_pk_bf16_f32 v74, v2, v3
	v_add_f32_e64 v0, v2, v0
	v_add_f32_e64 v1, v3, v1
	v_add_f32_e64 v2, v148, -v64
	v_add_f32_e64 v3, v149, -v64
	v_add_f32_e64 v0, v4, v0
	v_add_f32_e64 v1, v5, v1
	v_exp_f32_e32 v2, v2
	v_exp_f32_e32 v3, v3
	v_add_f32_e64 v6, v146, -v64
	v_add_f32_e64 v7, v147, -v64
	v_cvt_pk_bf16_f32 v75, v4, v5
	v_cvt_pk_bf16_f32 v76, v2, v3
	v_add_f32_e64 v0, v2, v0
	v_add_f32_e64 v1, v3, v1
	v_exp_f32_e32 v6, v6
	v_exp_f32_e32 v7, v7
	v_add_f32_e64 v2, v72, -v64
	v_add_f32_e64 v3, v73, -v64
	v_add_f32_e64 v4, v70, -v64
	v_add_f32_e64 v5, v71, -v64
	v_exp_f32_e32 v2, v2
	v_exp_f32_e32 v3, v3
	v_add_f32_e64 v0, v6, v0
	v_add_f32_e64 v1, v7, v1
	v_exp_f32_e32 v4, v4
	v_exp_f32_e32 v5, v5
	v_cvt_pk_bf16_f32 v77, v6, v7
	v_add_f32_e64 v0, v2, v0
	v_add_f32_e64 v1, v3, v1
	v_cvt_pk_bf16_f32 v70, v2, v3
	v_add_f32_e64 v2, v68, -v64
	v_add_f32_e64 v3, v69, -v64
	v_add_f32_e64 v6, v66, -v64
	v_add_f32_e64 v7, v67, -v64
	v_exp_f32_e32 v2, v2
	v_exp_f32_e32 v3, v3
	v_exp_f32_e32 v6, v6
	v_exp_f32_e32 v7, v7
	v_add_f32_e64 v0, v4, v0
	v_add_f32_e64 v1, v5, v1
	v_cvt_pk_bf16_f32 v71, v4, v5
	v_cvt_pk_bf16_f32 v72, v2, v3
	v_cvt_pk_bf16_f32 v73, v6, v7
	s_nop 0
	v_add_f32_e64 v0, v2, v0
	v_add_f32_e64 v1, v3, v1
	s_nop 0
	v_add_f32_e64 v78, v6, v0
	v_add_f32_e64 v79, v7, v1
	ds_read_b64_tr_b16 v[0:1], v170 offset:55296
	ds_read_b64_tr_b16 v[2:3], v170 offset:56448
	ds_read_b64_tr_b16 v[18:19], v170 offset:56512
	ds_read_b64_tr_b16 v[16:17], v170 offset:55360
	s_waitcnt lgkmcnt(2)
	v_mfma_f32_32x32x16_bf16 v[0:15], v[48:51], v[0:3], 0
	s_waitcnt lgkmcnt(0)
	v_mfma_f32_32x32x16_bf16 v[16:31], v[48:51], v[16:19], 0
	ds_read_b64_tr_b16 v[48:49], v170 offset:57600
	ds_read_b64_tr_b16 v[50:51], v170 offset:58752
	ds_read_b64_tr_b16 v[68:69], v170 offset:58816
	ds_read_b64_tr_b16 v[66:67], v170 offset:57664
	s_waitcnt lgkmcnt(2)
	v_mfma_f32_32x32x16_bf16 v[0:15], v[52:55], v[48:51], v[0:15]
	s_waitcnt lgkmcnt(0)
	v_mfma_f32_32x32x16_bf16 v[16:31], v[52:55], v[66:69], v[16:31]
	ds_read_b64_tr_b16 v[48:49], v170 offset:59904
	ds_read_b64_tr_b16 v[50:51], v170 offset:61056
	ds_read_b64_tr_b16 v[54:55], v170 offset:61120
	ds_read_b64_tr_b16 v[52:53], v170 offset:59968
	s_waitcnt lgkmcnt(2)
	v_mfma_f32_32x32x16_bf16 v[0:15], v[32:35], v[48:51], v[0:15]
	s_waitcnt lgkmcnt(0)
	v_mfma_f32_32x32x16_bf16 v[16:31], v[32:35], v[52:55], v[16:31]
	ds_read_b64_tr_b16 v[32:33], v170 offset:62208
	ds_read_b64_tr_b16 v[34:35], v170 offset:63360
	ds_read_b64_tr_b16 v[50:51], v170 offset:63424
	ds_read_b64_tr_b16 v[48:49], v170 offset:62272
	s_waitcnt lgkmcnt(2)
	v_mfma_f32_32x32x16_bf16 v[0:15], v[36:39], v[32:35], v[0:15]
	s_waitcnt lgkmcnt(0)
	v_mfma_f32_32x32x16_bf16 v[16:31], v[36:39], v[48:51], v[16:31]
	ds_read_b64_tr_b16 v[32:33], v170 offset:64512
	ds_read_b64_tr_b16 v[34:35], v171 offset:10368
	ds_read_b64_tr_b16 v[38:39], v171 offset:10432
	ds_read_b64_tr_b16 v[36:37], v170 offset:64576
	s_waitcnt lgkmcnt(2)
	v_mfma_f32_32x32x16_bf16 v[0:15], v[40:43], v[32:35], v[0:15]
	s_waitcnt lgkmcnt(0)
	v_mfma_f32_32x32x16_bf16 v[16:31], v[40:43], v[36:39], v[16:31]
	ds_read_b64_tr_b16 v[32:33], v171 offset:11520
	ds_read_b64_tr_b16 v[34:35], v171 offset:12672
	ds_read_b64_tr_b16 v[38:39], v171 offset:12736
	ds_read_b64_tr_b16 v[36:37], v171 offset:11584
	s_waitcnt lgkmcnt(2)
	v_mfma_f32_32x32x16_bf16 v[0:15], v[44:47], v[32:35], v[0:15]
	s_waitcnt lgkmcnt(0)
	v_mfma_f32_32x32x16_bf16 v[16:31], v[44:47], v[36:39], v[16:31]
	ds_read_b64_tr_b16 v[32:33], v171 offset:13824
	ds_read_b64_tr_b16 v[34:35], v171 offset:14976
	ds_read_b64_tr_b16 v[38:39], v171 offset:15040
	ds_read_b64_tr_b16 v[36:37], v171 offset:13888
	s_waitcnt lgkmcnt(2)
	v_mfma_f32_32x32x16_bf16 v[0:15], v[56:59], v[32:35], v[0:15]
	s_waitcnt lgkmcnt(0)
	v_mfma_f32_32x32x16_bf16 v[16:31], v[56:59], v[36:39], v[16:31]
	ds_read_b64_tr_b16 v[32:33], v171 offset:16128
	ds_read_b64_tr_b16 v[34:35], v171 offset:17280
	ds_read_b64_tr_b16 v[38:39], v171 offset:17344
	ds_read_b64_tr_b16 v[36:37], v171 offset:16192
	s_waitcnt lgkmcnt(2)
	v_mfma_f32_32x32x16_bf16 v[0:15], v[60:63], v[32:35], v[0:15]
	s_waitcnt lgkmcnt(0)
	v_mfma_f32_32x32x16_bf16 v[16:31], v[60:63], v[36:39], v[16:31]
	ds_read_b64_tr_b16 v[32:33], v171 offset:18432
	ds_read_b64_tr_b16 v[34:35], v171 offset:19584
	ds_read_b64_tr_b16 v[38:39], v171 offset:19648
	ds_read_b64_tr_b16 v[36:37], v171 offset:18496
	s_waitcnt lgkmcnt(2)
	v_mfma_f32_32x32x16_bf16 v[0:15], v[74:77], v[32:35], v[0:15]
	s_waitcnt lgkmcnt(0)
	v_mfma_f32_32x32x16_bf16 v[16:31], v[74:77], v[36:39], v[16:31]
	ds_read_b64_tr_b16 v[32:33], v171 offset:20736
	ds_read_b64_tr_b16 v[34:35], v171 offset:21888
	ds_read_b64_tr_b16 v[38:39], v171 offset:21952
	ds_read_b64_tr_b16 v[36:37], v171 offset:20800
	s_waitcnt lgkmcnt(2)
	v_mfma_f32_32x32x16_bf16 v[0:15], v[70:73], v[32:35], v[0:15]
	v_add_f32_e32 v32, v78, v79
	ds_bpermute_b32 v33, v65, v32
	s_waitcnt lgkmcnt(1)
	v_mfma_f32_32x32x16_bf16 v[16:31], v[70:73], v[36:39], v[16:31]
	s_and_saveexec_b64 s[60:61], s[10:11]
	s_cbranch_execz .LBB0_1228
	v_sub_f32_e32 v34, v97, v64
	v_exp_f32_e32 v34, v34
	s_waitcnt lgkmcnt(0)
	v_add_f32_e32 v32, v32, v33
	v_add_f32_e32 v32, v34, v32
	v_div_scale_f32 v33, s[88:89], v32, v32, 1.0
	v_rcp_f32_e32 v34, v33
	v_div_scale_f32 v35, vcc, 1.0, v32, 1.0
	v_fma_f32 v36, -v33, v34, 1.0
	v_fmac_f32_e32 v34, v36, v34
	v_mul_f32_e32 v36, v35, v34
	v_fma_f32 v37, -v33, v36, v35
	v_fmac_f32_e32 v36, v37, v34
	v_fma_f32 v33, -v33, v36, v35
	v_div_fmas_f32 v33, v33, v34, v36
	v_div_fixup_f32 v32, v33, v32, 1.0
	ds_write_b32 v188, v32 offset:4608
	s_branch .LBB0_1228

	.amdhsa_kernel _Z8yoco_fwd4Args
		.amdhsa_group_segment_fixed_size 0
		.amdhsa_private_segment_fixed_size 0
		.amdhsa_kernarg_size 376
		.amdhsa_user_sgpr_count 2
		.amdhsa_user_sgpr_dispatch_ptr 0
		.amdhsa_user_sgpr_queue_ptr 0
		.amdhsa_user_sgpr_kernarg_segment_ptr 1
		.amdhsa_user_sgpr_dispatch_id 0
		.amdhsa_user_sgpr_kernarg_preload_length 0
		.amdhsa_user_sgpr_kernarg_preload_offset 0
		.amdhsa_user_sgpr_private_segment_size 0
		.amdhsa_uses_dynamic_stack 0
		.amdhsa_enable_private_segment 0
		.amdhsa_system_sgpr_workgroup_id_x 1
		.amdhsa_system_sgpr_workgroup_id_y 0
		.amdhsa_system_sgpr_workgroup_id_z 0
		.amdhsa_system_sgpr_workgroup_info 0
		.amdhsa_system_vgpr_workitem_id 2
		.amdhsa_next_free_vgpr 232
		.amdhsa_next_free_sgpr 99
		.amdhsa_accum_offset 232
		.amdhsa_reserve_vcc 1
		.amdhsa_float_round_mode_32 0
		.amdhsa_float_round_mode_16_64 0
		.amdhsa_float_denorm_mode_32 3
		.amdhsa_float_denorm_mode_16_64 3
		.amdhsa_dx10_clamp 1
		.amdhsa_ieee_mode 1
		.amdhsa_fp16_overflow 0
		.amdhsa_tg_split 0
		.amdhsa_exception_fp_ieee_invalid_op 0
		.amdhsa_exception_fp_denorm_src 0
		.amdhsa_exception_fp_ieee_div_zero 0
		.amdhsa_exception_fp_ieee_overflow 0
		.amdhsa_exception_fp_ieee_underflow 0
		.amdhsa_exception_fp_ieee_inexact 0
		.amdhsa_exception_int_div_zero 0
	.end_amdhsa_kernel

amdhsa.kernels:
  - .agpr_count:     0
    .args:
      - .offset:         0
        .size:           120
        .value_kind:     by_value
      - .offset:         120
        .size:           4
        .value_kind:     hidden_block_count_x
      - .offset:         124
        .size:           4
        .value_kind:     hidden_block_count_y
      - .offset:         128
        .size:           4
        .value_kind:     hidden_block_count_z
      - .offset:         132
        .size:           2
        .value_kind:     hidden_group_size_x
      - .offset:         134
        .size:           2
        .value_kind:     hidden_group_size_y
      - .offset:         136
        .size:           2
        .value_kind:     hidden_group_size_z
      - .offset:         138
        .size:           2
        .value_kind:     hidden_remainder_x
      - .offset:         140
        .size:           2
        .value_kind:     hidden_remainder_y
      - .offset:         142
        .size:           2
        .value_kind:     hidden_remainder_z
      - .offset:         160
        .size:           8
        .value_kind:     hidden_global_offset_x
      - .offset:         168
        .size:           8
        .value_kind:     hidden_global_offset_y
      - .offset:         176
        .size:           8
        .value_kind:     hidden_global_offset_z
      - .offset:         184
        .size:           2
        .value_kind:     hidden_grid_dims
      - .offset:         208
        .size:           8
        .value_kind:     hidden_multigrid_sync_arg
      - .offset:         240
        .size:           4
        .value_kind:     hidden_dynamic_lds_size
    .group_segment_fixed_size: 0
    .kernarg_segment_align: 8
    .kernarg_segment_size: 376
    .language:       OpenCL C
    .language_version:
      - 2
      - 0
    .max_flat_workgroup_size: 512
    .name:           _Z8yoco_fwd4Args
    .private_segment_fixed_size: 0
    .sgpr_count:     105
    .sgpr_spill_count: 3
    .symbol:         _Z8yoco_fwd4Args.kd
    .uniform_work_group_size: 1
    .uses_dynamic_stack: false
    .vgpr_count:     232
    .vgpr_spill_count: 0
    .wavefront_size: 64
